# v102 + s_setprio 1 moved above the load-phase closing waits (no instruction between last wait and pre-MMA barrier)
# speedup vs baseline: 1.0054x; 1.0029x over previous
.LBB0_333:
	s_add_u32 s68, s56, s49
	s_addc_u32 s70, s57, 0
	s_add_u32 s64, s68, 0x100
	s_addc_u32 s65, s70, 0
	s_and_b64 s[62:63], s[60:61], exec
	s_cselect_b32 s65, s18, s65
	s_cselect_b32 s64, s19, s64
	s_add_u32 s49, s54, s49
	s_addc_u32 s62, s55, 0
	s_add_u32 s49, s49, 0x100
	s_addc_u32 s62, s62, 0
	s_add_i32 s80, 0, 0x10000
	s_and_b64 s[60:61], s[60:61], exec
	s_cselect_b32 s67, s33, s62
	s_cselect_b32 s66, s45, s49
	s_add_i32 s61, 0, 0x14000
	s_add_u32 s72, s68, 0x10080
	s_addc_u32 s73, s70, 0
	s_add_i32 s79, s80, s2
	s_add_i32 m0, s4, 0xc000
	s_add_i32 s82, s4, 0xe000
	s_add_i32 s76, s79, 0x2000
	s_add_u32 s70, s66, 0x10000
	v_add_u32_e32 v152, s80, v138
	v_add_u32_e32 v168, s61, v138
	s_addc_u32 s71, s67, 0
	s_add_i32 s78, s61, s2
	ds_read_b128 v[140:143], v152
	ds_read_b128 v[144:147], v152 offset:1024
	ds_read_b128 v[148:151], v152 offset:2048
	ds_read_b128 v[152:155], v152 offset:3072
	ds_read_b128 v[156:159], v168
	ds_read_b128 v[160:163], v168 offset:1024
	ds_read_b128 v[164:167], v168 offset:2048
	ds_read_b128 v[168:171], v168 offset:3072
	s_add_i32 s77, s78, 0x2000
	s_add_i32 s75, 0, 0x18000
	s_add_i32 s74, 0, 0x1c000
	s_add_u32 s62, s64, 0x10000
	s_addc_u32 s63, s65, 0
	s_add_i32 s68, s75, s2
	s_add_i32 s49, s68, 0x2000
	s_add_u32 s60, s66, 0x10080
	s_addc_u32 s61, s67, 0
	s_add_i32 s81, s74, s2
	s_add_i32 s80, s81, 0x2000
	v_lshl_add_u64 v[204:205], s[72:73], 0, v[136:137]
	ds_read_b128 v[172:175], v139
	ds_read_b128 v[176:179], v139 offset:1024
	ds_read_b128 v[180:183], v139 offset:2048
	ds_read_b128 v[184:187], v139 offset:3072
	ds_read_b128 v[188:191], v139 offset:4096
	ds_read_b128 v[192:195], v139 offset:5120
	ds_read_b128 v[196:199], v139 offset:6144
	ds_read_b128 v[214:217], v139 offset:7168
	global_load_lds_dwordx4 v[204:205], off
	v_lshl_add_u64 v[204:205], s[72:73], 0, v[134:135]
	s_mov_b32 m0, s82
	s_nop 0
	global_load_lds_dwordx4 v[204:205], off
	s_setprio 1
	s_waitcnt vmcnt(8)
	s_waitcnt lgkmcnt(0)
	s_barrier
	v_mfma_f32_16x16x32_bf16 v[128:131], v[140:143], v[172:175], v[128:131]
	v_mfma_f32_16x16x32_bf16 v[124:127], v[148:151], v[172:175], v[124:127]
	v_mfma_f32_16x16x32_bf16 v[120:123], v[140:143], v[180:183], v[120:123]
	v_mfma_f32_16x16x32_bf16 v[116:119], v[148:151], v[180:183], v[116:119]
	v_mfma_f32_16x16x32_bf16 v[104:107], v[140:143], v[188:191], v[104:107]
	v_mfma_f32_16x16x32_bf16 v[100:103], v[148:151], v[188:191], v[100:103]
	v_mfma_f32_16x16x32_bf16 v[86:89], v[140:143], v[196:199], v[86:89]
	v_mfma_f32_16x16x32_bf16 v[82:85], v[148:151], v[196:199], v[82:85]
	v_mfma_f32_16x16x32_bf16 v[128:131], v[144:147], v[176:179], v[128:131]
	v_mfma_f32_16x16x32_bf16 v[124:127], v[152:155], v[176:179], v[124:127]
	v_mfma_f32_16x16x32_bf16 v[120:123], v[144:147], v[184:187], v[120:123]
	v_mfma_f32_16x16x32_bf16 v[116:119], v[152:155], v[184:187], v[116:119]
	v_mfma_f32_16x16x32_bf16 v[104:107], v[144:147], v[192:195], v[104:107]
	v_mfma_f32_16x16x32_bf16 v[100:103], v[152:155], v[192:195], v[100:103]
	v_mfma_f32_16x16x32_bf16 v[86:89], v[144:147], v[214:217], v[86:89]
	v_mfma_f32_16x16x32_bf16 v[82:85], v[152:155], v[214:217], v[82:85]
	s_setprio 0
	s_setprio 1
	v_mfma_f32_16x16x32_bf16 v[112:115], v[156:159], v[172:175], v[112:115]
	v_mfma_f32_16x16x32_bf16 v[108:111], v[164:167], v[172:175], v[108:111]
	v_mfma_f32_16x16x32_bf16 v[94:97], v[156:159], v[180:183], v[94:97]
	v_mfma_f32_16x16x32_bf16 v[90:93], v[164:167], v[180:183], v[90:93]
	v_mfma_f32_16x16x32_bf16 v[78:81], v[156:159], v[188:191], v[78:81]
	v_mfma_f32_16x16x32_bf16 v[74:77], v[164:167], v[188:191], v[74:77]
	v_mfma_f32_16x16x32_bf16 v[70:73], v[156:159], v[196:199], v[70:73]
	v_mfma_f32_16x16x32_bf16 v[66:69], v[164:167], v[196:199], v[66:69]
	v_mfma_f32_16x16x32_bf16 v[112:115], v[160:163], v[176:179], v[112:115]
	v_mfma_f32_16x16x32_bf16 v[108:111], v[168:171], v[176:179], v[108:111]
	v_mfma_f32_16x16x32_bf16 v[94:97], v[160:163], v[184:187], v[94:97]
	v_mfma_f32_16x16x32_bf16 v[90:93], v[168:171], v[184:187], v[90:93]
	v_mfma_f32_16x16x32_bf16 v[78:81], v[160:163], v[192:195], v[78:81]
	v_mfma_f32_16x16x32_bf16 v[74:77], v[168:171], v[192:195], v[74:77]
	v_mfma_f32_16x16x32_bf16 v[70:73], v[160:163], v[214:217], v[70:73]
	v_mfma_f32_16x16x32_bf16 v[66:69], v[168:171], v[214:217], v[66:69]
	s_setprio 0
	s_barrier
	s_mov_b32 m0, s79
	v_lshl_add_u64 v[204:205], s[66:67], 0, v[98:99]
	ds_read_b128 v[172:175], v139 offset:16384
	ds_read_b128 v[176:179], v139 offset:17408
	ds_read_b128 v[180:183], v139 offset:18432
	ds_read_b128 v[184:187], v139 offset:19456
	ds_read_b128 v[188:191], v139 offset:20480
	ds_read_b128 v[192:195], v139 offset:21504
	ds_read_b128 v[196:199], v139 offset:22528
	ds_read_b128 v[214:217], v139 offset:23552
	global_load_lds_dwordx4 v[204:205], off
	v_lshl_add_u64 v[206:207], s[66:67], 0, v[132:133]
	s_mov_b32 m0, s76
	v_lshl_add_u64 v[208:209], s[70:71], 0, v[98:99]
	global_load_lds_dwordx4 v[206:207], off
	s_mov_b32 m0, s78
	v_lshl_add_u64 v[210:211], s[64:65], 0, v[134:135]
	global_load_lds_dwordx4 v[208:209], off
	v_lshl_add_u64 v[208:209], s[70:71], 0, v[132:133]
	s_mov_b32 m0, s77
	s_nop 0
	global_load_lds_dwordx4 v[208:209], off
	v_lshl_add_u64 v[208:209], s[64:65], 0, v[136:137]
	s_mov_b32 m0, s4
	s_nop 0
	global_load_lds_dwordx4 v[208:209], off
	s_mov_b32 m0, s7
	s_nop 0
	global_load_lds_dwordx4 v[210:211], off
	s_setprio 1
	s_waitcnt vmcnt(8)
	s_waitcnt lgkmcnt(0)
	s_barrier
	v_mfma_f32_16x16x32_bf16 v[62:65], v[140:143], v[172:175], v[62:65]
	v_mfma_f32_16x16x32_bf16 v[58:61], v[148:151], v[172:175], v[58:61]
	v_mfma_f32_16x16x32_bf16 v[54:57], v[140:143], v[180:183], v[54:57]
	v_mfma_f32_16x16x32_bf16 v[50:53], v[148:151], v[180:183], v[50:53]
	v_mfma_f32_16x16x32_bf16 v[38:41], v[140:143], v[188:191], v[38:41]
	v_mfma_f32_16x16x32_bf16 v[34:37], v[148:151], v[188:191], v[34:37]
	v_mfma_f32_16x16x32_bf16 v[22:25], v[140:143], v[196:199], v[22:25]
	v_mfma_f32_16x16x32_bf16 v[18:21], v[148:151], v[196:199], v[18:21]
	v_mfma_f32_16x16x32_bf16 v[62:65], v[144:147], v[176:179], v[62:65]
	v_mfma_f32_16x16x32_bf16 v[58:61], v[152:155], v[176:179], v[58:61]
	v_mfma_f32_16x16x32_bf16 v[54:57], v[144:147], v[184:187], v[54:57]
	v_mfma_f32_16x16x32_bf16 v[50:53], v[152:155], v[184:187], v[50:53]
	v_mfma_f32_16x16x32_bf16 v[38:41], v[144:147], v[192:195], v[38:41]
	v_mfma_f32_16x16x32_bf16 v[34:37], v[152:155], v[192:195], v[34:37]
	v_mfma_f32_16x16x32_bf16 v[22:25], v[144:147], v[214:217], v[22:25]
	v_mfma_f32_16x16x32_bf16 v[18:21], v[152:155], v[214:217], v[18:21]
	s_setprio 0
	s_setprio 1
	v_mfma_f32_16x16x32_bf16 v[46:49], v[156:159], v[172:175], v[46:49]
	v_mfma_f32_16x16x32_bf16 v[42:45], v[164:167], v[172:175], v[42:45]
	v_mfma_f32_16x16x32_bf16 v[30:33], v[156:159], v[180:183], v[30:33]
	v_mfma_f32_16x16x32_bf16 v[26:29], v[164:167], v[180:183], v[26:29]
	v_mfma_f32_16x16x32_bf16 v[14:17], v[156:159], v[188:191], v[14:17]
	v_mfma_f32_16x16x32_bf16 v[10:13], v[164:167], v[188:191], v[10:13]
	v_mfma_f32_16x16x32_bf16 v[6:9], v[156:159], v[196:199], v[6:9]
	v_mfma_f32_16x16x32_bf16 v[2:5], v[164:167], v[196:199], v[2:5]
	v_mfma_f32_16x16x32_bf16 v[46:49], v[160:163], v[176:179], v[46:49]
	v_mfma_f32_16x16x32_bf16 v[42:45], v[168:171], v[176:179], v[42:45]
	v_mfma_f32_16x16x32_bf16 v[30:33], v[160:163], v[184:187], v[30:33]
	v_mfma_f32_16x16x32_bf16 v[26:29], v[168:171], v[184:187], v[26:29]
	v_mfma_f32_16x16x32_bf16 v[14:17], v[160:163], v[192:195], v[14:17]
	v_mfma_f32_16x16x32_bf16 v[10:13], v[168:171], v[192:195], v[10:13]
	v_mfma_f32_16x16x32_bf16 v[6:9], v[160:163], v[214:217], v[6:9]
	v_mfma_f32_16x16x32_bf16 v[2:5], v[168:171], v[214:217], v[2:5]
	s_setprio 0
	s_barrier
	v_add_u32_e32 v152, s75, v138
	v_add_u32_e32 v168, s74, v138
	ds_read_b128 v[140:143], v152
	ds_read_b128 v[144:147], v152 offset:1024
	ds_read_b128 v[148:151], v152 offset:2048
	ds_read_b128 v[152:155], v152 offset:3072
	ds_read_b128 v[156:159], v168
	ds_read_b128 v[160:163], v168 offset:1024
	ds_read_b128 v[164:167], v168 offset:2048
	ds_read_b128 v[168:171], v168 offset:3072
	s_mov_b32 m0, s8
	v_lshl_add_u64 v[218:219], s[62:63], 0, v[136:137]
	ds_read_b128 v[172:175], v139 offset:32768
	ds_read_b128 v[176:179], v139 offset:33792
	ds_read_b128 v[180:183], v139 offset:34816
	ds_read_b128 v[184:187], v139 offset:35840
	ds_read_b128 v[188:191], v139 offset:36864
	ds_read_b128 v[192:195], v139 offset:37888
	ds_read_b128 v[196:199], v139 offset:38912
	ds_read_b128 v[214:217], v139 offset:39936
	global_load_lds_dwordx4 v[218:219], off
	v_lshl_add_u64 v[218:219], s[62:63], 0, v[134:135]
	s_mov_b32 m0, s9
	s_nop 0
	global_load_lds_dwordx4 v[218:219], off
	s_setprio 1
	s_waitcnt vmcnt(8)
	s_waitcnt lgkmcnt(0)
	s_barrier
	v_mfma_f32_16x16x32_bf16 v[128:131], v[140:143], v[172:175], v[128:131]
	v_mfma_f32_16x16x32_bf16 v[124:127], v[148:151], v[172:175], v[124:127]
	v_mfma_f32_16x16x32_bf16 v[120:123], v[140:143], v[180:183], v[120:123]
	v_mfma_f32_16x16x32_bf16 v[116:119], v[148:151], v[180:183], v[116:119]
	v_mfma_f32_16x16x32_bf16 v[104:107], v[140:143], v[188:191], v[104:107]
	v_mfma_f32_16x16x32_bf16 v[100:103], v[148:151], v[188:191], v[100:103]
	v_mfma_f32_16x16x32_bf16 v[86:89], v[140:143], v[196:199], v[86:89]
	v_mfma_f32_16x16x32_bf16 v[82:85], v[148:151], v[196:199], v[82:85]
	v_mfma_f32_16x16x32_bf16 v[128:131], v[144:147], v[176:179], v[128:131]
	v_mfma_f32_16x16x32_bf16 v[124:127], v[152:155], v[176:179], v[124:127]
	v_mfma_f32_16x16x32_bf16 v[120:123], v[144:147], v[184:187], v[120:123]
	v_mfma_f32_16x16x32_bf16 v[116:119], v[152:155], v[184:187], v[116:119]
	v_mfma_f32_16x16x32_bf16 v[104:107], v[144:147], v[192:195], v[104:107]
	v_mfma_f32_16x16x32_bf16 v[100:103], v[152:155], v[192:195], v[100:103]
	v_mfma_f32_16x16x32_bf16 v[86:89], v[144:147], v[214:217], v[86:89]
	v_mfma_f32_16x16x32_bf16 v[82:85], v[152:155], v[214:217], v[82:85]
	s_setprio 0
	s_setprio 1
	v_mfma_f32_16x16x32_bf16 v[112:115], v[156:159], v[172:175], v[112:115]
	v_mfma_f32_16x16x32_bf16 v[108:111], v[164:167], v[172:175], v[108:111]
	v_mfma_f32_16x16x32_bf16 v[94:97], v[156:159], v[180:183], v[94:97]
	v_mfma_f32_16x16x32_bf16 v[90:93], v[164:167], v[180:183], v[90:93]
	v_mfma_f32_16x16x32_bf16 v[78:81], v[156:159], v[188:191], v[78:81]
	v_mfma_f32_16x16x32_bf16 v[74:77], v[164:167], v[188:191], v[74:77]
	v_mfma_f32_16x16x32_bf16 v[70:73], v[156:159], v[196:199], v[70:73]
	v_mfma_f32_16x16x32_bf16 v[66:69], v[164:167], v[196:199], v[66:69]
	v_mfma_f32_16x16x32_bf16 v[112:115], v[160:163], v[176:179], v[112:115]
	v_mfma_f32_16x16x32_bf16 v[108:111], v[168:171], v[176:179], v[108:111]
	v_mfma_f32_16x16x32_bf16 v[94:97], v[160:163], v[184:187], v[94:97]
	v_mfma_f32_16x16x32_bf16 v[90:93], v[168:171], v[184:187], v[90:93]
	v_mfma_f32_16x16x32_bf16 v[78:81], v[160:163], v[192:195], v[78:81]
	v_mfma_f32_16x16x32_bf16 v[74:77], v[168:171], v[192:195], v[74:77]
	v_mfma_f32_16x16x32_bf16 v[70:73], v[160:163], v[214:217], v[70:73]
	v_mfma_f32_16x16x32_bf16 v[66:69], v[168:171], v[214:217], v[66:69]
	s_setprio 0
	s_barrier
	s_mov_b32 m0, s68
	v_lshl_add_u64 v[204:205], v[204:205], 0, s[28:29]
	ds_read_b128 v[172:175], v139 offset:49152
	ds_read_b128 v[176:179], v139 offset:50176
	ds_read_b128 v[180:183], v139 offset:51200
	ds_read_b128 v[184:187], v139 offset:52224
	ds_read_b128 v[188:191], v139 offset:53248
	ds_read_b128 v[192:195], v139 offset:54272
	ds_read_b128 v[196:199], v139 offset:55296
	ds_read_b128 v[214:217], v139 offset:56320
	global_load_lds_dwordx4 v[204:205], off
	v_lshl_add_u64 v[204:205], v[206:207], 0, s[28:29]
	s_mov_b32 m0, s49
	s_nop 0
	global_load_lds_dwordx4 v[204:205], off
	v_lshl_add_u64 v[204:205], s[60:61], 0, v[98:99]
	s_mov_b32 m0, s81
	s_nop 0
	global_load_lds_dwordx4 v[204:205], off
	v_lshl_add_u64 v[204:205], s[60:61], 0, v[132:133]
	s_mov_b32 m0, s80
	s_nop 0
	global_load_lds_dwordx4 v[204:205], off
	v_lshl_add_u64 v[204:205], v[208:209], 0, s[28:29]
	s_mov_b32 m0, s10
	s_nop 0
	global_load_lds_dwordx4 v[204:205], off
	v_lshl_add_u64 v[204:205], v[210:211], 0, s[28:29]
	s_mov_b32 m0, s11
	s_nop 0
	global_load_lds_dwordx4 v[204:205], off
	s_setprio 1
	s_waitcnt vmcnt(8)
	s_waitcnt lgkmcnt(0)
	s_barrier
	v_mfma_f32_16x16x32_bf16 v[62:65], v[140:143], v[172:175], v[62:65]
	v_mfma_f32_16x16x32_bf16 v[58:61], v[148:151], v[172:175], v[58:61]
	v_mfma_f32_16x16x32_bf16 v[54:57], v[140:143], v[180:183], v[54:57]
	v_mfma_f32_16x16x32_bf16 v[50:53], v[148:151], v[180:183], v[50:53]
	v_mfma_f32_16x16x32_bf16 v[38:41], v[140:143], v[188:191], v[38:41]
	v_mfma_f32_16x16x32_bf16 v[34:37], v[148:151], v[188:191], v[34:37]
	v_mfma_f32_16x16x32_bf16 v[22:25], v[140:143], v[196:199], v[22:25]
	v_mfma_f32_16x16x32_bf16 v[18:21], v[148:151], v[196:199], v[18:21]
	v_mfma_f32_16x16x32_bf16 v[62:65], v[144:147], v[176:179], v[62:65]
	v_mfma_f32_16x16x32_bf16 v[58:61], v[152:155], v[176:179], v[58:61]
	v_mfma_f32_16x16x32_bf16 v[54:57], v[144:147], v[184:187], v[54:57]
	v_mfma_f32_16x16x32_bf16 v[50:53], v[152:155], v[184:187], v[50:53]
	v_mfma_f32_16x16x32_bf16 v[38:41], v[144:147], v[192:195], v[38:41]
	v_mfma_f32_16x16x32_bf16 v[34:37], v[152:155], v[192:195], v[34:37]
	v_mfma_f32_16x16x32_bf16 v[22:25], v[144:147], v[214:217], v[22:25]
	v_mfma_f32_16x16x32_bf16 v[18:21], v[152:155], v[214:217], v[18:21]
	s_setprio 0
	s_setprio 1
	v_mfma_f32_16x16x32_bf16 v[46:49], v[156:159], v[172:175], v[46:49]
	v_mfma_f32_16x16x32_bf16 v[42:45], v[164:167], v[172:175], v[42:45]
	v_mfma_f32_16x16x32_bf16 v[30:33], v[156:159], v[180:183], v[30:33]
	v_mfma_f32_16x16x32_bf16 v[26:29], v[164:167], v[180:183], v[26:29]
	v_mfma_f32_16x16x32_bf16 v[14:17], v[156:159], v[188:191], v[14:17]
	v_mfma_f32_16x16x32_bf16 v[10:13], v[164:167], v[188:191], v[10:13]
	v_mfma_f32_16x16x32_bf16 v[6:9], v[156:159], v[196:199], v[6:9]
	v_mfma_f32_16x16x32_bf16 v[2:5], v[164:167], v[196:199], v[2:5]
	v_mfma_f32_16x16x32_bf16 v[46:49], v[160:163], v[176:179], v[46:49]
	v_mfma_f32_16x16x32_bf16 v[42:45], v[168:171], v[176:179], v[42:45]
	v_mfma_f32_16x16x32_bf16 v[30:33], v[160:163], v[184:187], v[30:33]
	v_mfma_f32_16x16x32_bf16 v[26:29], v[168:171], v[184:187], v[26:29]
	v_mfma_f32_16x16x32_bf16 v[14:17], v[160:163], v[192:195], v[14:17]
	v_mfma_f32_16x16x32_bf16 v[10:13], v[168:171], v[192:195], v[10:13]
	v_mfma_f32_16x16x32_bf16 v[6:9], v[160:163], v[214:217], v[6:9]
	v_mfma_f32_16x16x32_bf16 v[2:5], v[168:171], v[214:217], v[2:5]
	s_setprio 0
	s_barrier
	s_movk_i32 s49, 0x100
	s_andn2_b64 vcc, exec, s[58:59]
	s_mov_b64 s[60:61], -1
	s_mov_b64 s[58:59], 0
	s_cbranch_vccz .LBB0_333
	s_and_b64 vcc, exec, s[40:41]
	s_cbranch_vccz .LBB0_336
	s_barrier

.LBB0_438:
	s_add_u32 s42, s40, 0xfffc0080
	s_addc_u32 s43, s41, -1
	s_add_i32 s67, 0, 0x10000
	s_cmp_eq_u32 s66, 12
	s_cselect_b32 s45, s1, s43
	s_cselect_b32 s44, s49, s42
	s_cselect_b32 s43, s55, s65
	s_cselect_b32 s42, s63, s64
	s_add_i32 s72, 0, 0x14000
	v_add_u32_e32 v108, s67, v162
	v_add_u32_e32 v160, s72, v162
	ds_read_b128 v[90:93], v108
	ds_read_b128 v[94:97], v108 offset:1024
	ds_read_b128 v[100:103], v108 offset:2048
	ds_read_b128 v[108:111], v108 offset:3072
	ds_read_b128 v[166:169], v160
	ds_read_b128 v[170:173], v160 offset:1024
	ds_read_b128 v[174:177], v160 offset:2048
	ds_read_b128 v[178:181], v160 offset:3072
	v_lshl_add_u64 v[160:161], s[40:41], 0, v[156:157]
	s_add_i32 m0, s8, 0xc000
	ds_read_b128 v[182:185], v163
	ds_read_b128 v[186:189], v163 offset:1024
	ds_read_b128 v[190:193], v163 offset:2048
	ds_read_b128 v[194:197], v163 offset:3072
	ds_read_b128 v[214:217], v163 offset:4096
	ds_read_b128 v[218:221], v163 offset:5120
	ds_read_b128 v[222:225], v163 offset:6144
	ds_read_b128 v[226:229], v163 offset:7168
	global_load_lds_dwordx4 v[160:161], off
	v_lshl_add_u64 v[160:161], s[40:41], 0, v[158:159]
	s_add_i32 m0, s8, 0xe000
	s_nop 0
	global_load_lds_dwordx4 v[160:161], off
	s_setprio 1
	s_waitcnt vmcnt(8)
	s_waitcnt lgkmcnt(0)
	s_barrier
	v_mfma_f32_16x16x32_bf16 v[144:147], v[90:93], v[182:185], v[144:147]
	v_mfma_f32_16x16x32_bf16 v[140:143], v[100:103], v[182:185], v[140:143]
	v_mfma_f32_16x16x32_bf16 v[128:131], v[90:93], v[190:193], v[128:131]
	v_mfma_f32_16x16x32_bf16 v[124:127], v[100:103], v[190:193], v[124:127]
	v_mfma_f32_16x16x32_bf16 v[112:115], v[90:93], v[214:217], v[112:115]
	v_mfma_f32_16x16x32_bf16 v[104:107], v[100:103], v[214:217], v[104:107]
	v_mfma_f32_16x16x32_bf16 v[78:81], v[90:93], v[222:225], v[78:81]
	v_mfma_f32_16x16x32_bf16 v[74:77], v[100:103], v[222:225], v[74:77]
	v_mfma_f32_16x16x32_bf16 v[144:147], v[94:97], v[186:189], v[144:147]
	v_mfma_f32_16x16x32_bf16 v[140:143], v[108:111], v[186:189], v[140:143]
	v_mfma_f32_16x16x32_bf16 v[128:131], v[94:97], v[194:197], v[128:131]
	v_mfma_f32_16x16x32_bf16 v[124:127], v[108:111], v[194:197], v[124:127]
	v_mfma_f32_16x16x32_bf16 v[112:115], v[94:97], v[218:221], v[112:115]
	v_mfma_f32_16x16x32_bf16 v[104:107], v[108:111], v[218:221], v[104:107]
	v_mfma_f32_16x16x32_bf16 v[78:81], v[94:97], v[226:229], v[78:81]
	v_mfma_f32_16x16x32_bf16 v[74:77], v[108:111], v[226:229], v[74:77]
	s_setprio 0
	s_setprio 1
	v_mfma_f32_16x16x32_bf16 v[136:139], v[166:169], v[182:185], v[136:139]
	v_mfma_f32_16x16x32_bf16 v[132:135], v[174:177], v[182:185], v[132:135]
	v_mfma_f32_16x16x32_bf16 v[120:123], v[166:169], v[190:193], v[120:123]
	v_mfma_f32_16x16x32_bf16 v[116:119], v[174:177], v[190:193], v[116:119]
	v_mfma_f32_16x16x32_bf16 v[86:89], v[166:169], v[214:217], v[86:89]
	v_mfma_f32_16x16x32_bf16 v[82:85], v[174:177], v[214:217], v[82:85]
	v_mfma_f32_16x16x32_bf16 v[70:73], v[166:169], v[222:225], v[70:73]
	v_mfma_f32_16x16x32_bf16 v[66:69], v[174:177], v[222:225], v[66:69]
	v_mfma_f32_16x16x32_bf16 v[136:139], v[170:173], v[186:189], v[136:139]
	v_mfma_f32_16x16x32_bf16 v[132:135], v[178:181], v[186:189], v[132:135]
	v_mfma_f32_16x16x32_bf16 v[120:123], v[170:173], v[194:197], v[120:123]
	v_mfma_f32_16x16x32_bf16 v[116:119], v[178:181], v[194:197], v[116:119]
	v_mfma_f32_16x16x32_bf16 v[86:89], v[170:173], v[218:221], v[86:89]
	v_mfma_f32_16x16x32_bf16 v[82:85], v[178:181], v[218:221], v[82:85]
	v_mfma_f32_16x16x32_bf16 v[70:73], v[170:173], v[226:229], v[70:73]
	v_mfma_f32_16x16x32_bf16 v[66:69], v[178:181], v[226:229], v[66:69]
	s_setprio 0
	s_barrier
	s_add_i32 s67, s67, s7
	v_lshl_add_u64 v[160:161], s[42:43], 0, v[98:99]
	s_mov_b32 m0, s67
	ds_read_b128 v[182:185], v163 offset:16384
	ds_read_b128 v[186:189], v163 offset:17408
	ds_read_b128 v[190:193], v163 offset:18432
	ds_read_b128 v[194:197], v163 offset:19456
	ds_read_b128 v[214:217], v163 offset:20480
	ds_read_b128 v[218:221], v163 offset:21504
	ds_read_b128 v[222:225], v163 offset:22528
	ds_read_b128 v[226:229], v163 offset:23552
	global_load_lds_dwordx4 v[160:161], off
	s_add_i32 m0, s67, 0x2000
	s_add_u32 s70, s42, 0x40000
	v_lshl_add_u64 v[198:199], s[42:43], 0, v[152:153]
	s_addc_u32 s71, s43, 0
	s_add_i32 s67, s72, s7
	global_load_lds_dwordx4 v[198:199], off
	v_lshl_add_u64 v[204:205], s[70:71], 0, v[98:99]
	s_mov_b32 m0, s67
	v_lshl_add_u64 v[206:207], s[44:45], 0, v[150:151]
	global_load_lds_dwordx4 v[204:205], off
	v_lshl_add_u64 v[204:205], s[70:71], 0, v[152:153]
	s_add_i32 m0, s67, 0x2000
	s_nop 0
	global_load_lds_dwordx4 v[204:205], off
	v_lshl_add_u64 v[204:205], s[44:45], 0, v[148:149]
	s_mov_b32 m0, s8
	s_nop 0
	global_load_lds_dwordx4 v[204:205], off
	s_mov_b32 m0, s9
	s_nop 0
	global_load_lds_dwordx4 v[206:207], off
	s_setprio 1
	s_waitcnt vmcnt(8)
	s_waitcnt lgkmcnt(0)
	s_barrier
	v_mfma_f32_16x16x32_bf16 v[62:65], v[90:93], v[182:185], v[62:65]
	v_mfma_f32_16x16x32_bf16 v[58:61], v[100:103], v[182:185], v[58:61]
	v_mfma_f32_16x16x32_bf16 v[46:49], v[90:93], v[190:193], v[46:49]
	v_mfma_f32_16x16x32_bf16 v[42:45], v[100:103], v[190:193], v[42:45]
	v_mfma_f32_16x16x32_bf16 v[30:33], v[90:93], v[214:217], v[30:33]
	v_mfma_f32_16x16x32_bf16 v[26:29], v[100:103], v[214:217], v[26:29]
	v_mfma_f32_16x16x32_bf16 v[14:17], v[90:93], v[222:225], v[14:17]
	v_mfma_f32_16x16x32_bf16 v[10:13], v[100:103], v[222:225], v[10:13]
	v_mfma_f32_16x16x32_bf16 v[62:65], v[94:97], v[186:189], v[62:65]
	v_mfma_f32_16x16x32_bf16 v[58:61], v[108:111], v[186:189], v[58:61]
	v_mfma_f32_16x16x32_bf16 v[46:49], v[94:97], v[194:197], v[46:49]
	v_mfma_f32_16x16x32_bf16 v[42:45], v[108:111], v[194:197], v[42:45]
	v_mfma_f32_16x16x32_bf16 v[30:33], v[94:97], v[218:221], v[30:33]
	v_mfma_f32_16x16x32_bf16 v[26:29], v[108:111], v[218:221], v[26:29]
	v_mfma_f32_16x16x32_bf16 v[14:17], v[94:97], v[226:229], v[14:17]
	v_mfma_f32_16x16x32_bf16 v[10:13], v[108:111], v[226:229], v[10:13]
	s_setprio 0
	s_setprio 1
	v_mfma_f32_16x16x32_bf16 v[54:57], v[166:169], v[182:185], v[54:57]
	v_mfma_f32_16x16x32_bf16 v[50:53], v[174:177], v[182:185], v[50:53]
	v_mfma_f32_16x16x32_bf16 v[38:41], v[166:169], v[190:193], v[38:41]
	v_mfma_f32_16x16x32_bf16 v[34:37], v[174:177], v[190:193], v[34:37]
	v_mfma_f32_16x16x32_bf16 v[22:25], v[166:169], v[214:217], v[22:25]
	v_mfma_f32_16x16x32_bf16 v[18:21], v[174:177], v[214:217], v[18:21]
	v_mfma_f32_16x16x32_bf16 v[6:9], v[166:169], v[222:225], v[6:9]
	v_mfma_f32_16x16x32_bf16 v[2:5], v[174:177], v[222:225], v[2:5]
	v_mfma_f32_16x16x32_bf16 v[54:57], v[170:173], v[186:189], v[54:57]
	v_mfma_f32_16x16x32_bf16 v[50:53], v[178:181], v[186:189], v[50:53]
	v_mfma_f32_16x16x32_bf16 v[38:41], v[170:173], v[194:197], v[38:41]
	v_mfma_f32_16x16x32_bf16 v[34:37], v[178:181], v[194:197], v[34:37]
	v_mfma_f32_16x16x32_bf16 v[22:25], v[170:173], v[218:221], v[22:25]
	v_mfma_f32_16x16x32_bf16 v[18:21], v[178:181], v[218:221], v[18:21]
	v_mfma_f32_16x16x32_bf16 v[6:9], v[170:173], v[226:229], v[6:9]
	v_mfma_f32_16x16x32_bf16 v[2:5], v[178:181], v[226:229], v[2:5]
	s_setprio 0
	s_barrier
	s_add_i32 s67, 0, 0x18000
	s_add_i32 s70, 0, 0x1c000
	v_add_u32_e32 v108, s67, v162
	v_add_u32_e32 v165, s70, v162
	ds_read_b128 v[90:93], v108
	ds_read_b128 v[94:97], v108 offset:1024
	ds_read_b128 v[100:103], v108 offset:2048
	ds_read_b128 v[108:111], v108 offset:3072
	ds_read_b128 v[166:169], v165
	ds_read_b128 v[170:173], v165 offset:1024
	ds_read_b128 v[174:177], v165 offset:2048
	ds_read_b128 v[178:181], v165 offset:3072
	s_add_u32 s44, s44, 0x40000
	s_addc_u32 s45, s45, 0
	s_mov_b32 m0, s10
	v_lshl_add_u64 v[208:209], s[44:45], 0, v[148:149]
	ds_read_b128 v[182:185], v163 offset:32768
	ds_read_b128 v[186:189], v163 offset:33792
	ds_read_b128 v[190:193], v163 offset:34816
	ds_read_b128 v[194:197], v163 offset:35840
	ds_read_b128 v[214:217], v163 offset:36864
	ds_read_b128 v[218:221], v163 offset:37888
	ds_read_b128 v[222:225], v163 offset:38912
	ds_read_b128 v[226:229], v163 offset:39936
	global_load_lds_dwordx4 v[208:209], off
	v_lshl_add_u64 v[208:209], s[44:45], 0, v[150:151]
	s_mov_b32 m0, s11
	s_nop 0
	global_load_lds_dwordx4 v[208:209], off
	s_setprio 1
	s_waitcnt vmcnt(8)
	s_waitcnt lgkmcnt(0)
	s_barrier
	v_mfma_f32_16x16x32_bf16 v[144:147], v[90:93], v[182:185], v[144:147]
	v_mfma_f32_16x16x32_bf16 v[140:143], v[100:103], v[182:185], v[140:143]
	v_mfma_f32_16x16x32_bf16 v[128:131], v[90:93], v[190:193], v[128:131]
	v_mfma_f32_16x16x32_bf16 v[124:127], v[100:103], v[190:193], v[124:127]
	v_mfma_f32_16x16x32_bf16 v[112:115], v[90:93], v[214:217], v[112:115]
	v_mfma_f32_16x16x32_bf16 v[104:107], v[100:103], v[214:217], v[104:107]
	v_mfma_f32_16x16x32_bf16 v[78:81], v[90:93], v[222:225], v[78:81]
	v_mfma_f32_16x16x32_bf16 v[74:77], v[100:103], v[222:225], v[74:77]
	v_mfma_f32_16x16x32_bf16 v[144:147], v[94:97], v[186:189], v[144:147]
	v_mfma_f32_16x16x32_bf16 v[140:143], v[108:111], v[186:189], v[140:143]
	v_mfma_f32_16x16x32_bf16 v[128:131], v[94:97], v[194:197], v[128:131]
	v_mfma_f32_16x16x32_bf16 v[124:127], v[108:111], v[194:197], v[124:127]
	v_mfma_f32_16x16x32_bf16 v[112:115], v[94:97], v[218:221], v[112:115]
	v_mfma_f32_16x16x32_bf16 v[104:107], v[108:111], v[218:221], v[104:107]
	v_mfma_f32_16x16x32_bf16 v[78:81], v[94:97], v[226:229], v[78:81]
	v_mfma_f32_16x16x32_bf16 v[74:77], v[108:111], v[226:229], v[74:77]
	s_setprio 0
	s_setprio 1
	v_mfma_f32_16x16x32_bf16 v[136:139], v[166:169], v[182:185], v[136:139]
	v_mfma_f32_16x16x32_bf16 v[132:135], v[174:177], v[182:185], v[132:135]
	v_mfma_f32_16x16x32_bf16 v[120:123], v[166:169], v[190:193], v[120:123]
	v_mfma_f32_16x16x32_bf16 v[116:119], v[174:177], v[190:193], v[116:119]
	v_mfma_f32_16x16x32_bf16 v[86:89], v[166:169], v[214:217], v[86:89]
	v_mfma_f32_16x16x32_bf16 v[82:85], v[174:177], v[214:217], v[82:85]
	v_mfma_f32_16x16x32_bf16 v[70:73], v[166:169], v[222:225], v[70:73]
	v_mfma_f32_16x16x32_bf16 v[66:69], v[174:177], v[222:225], v[66:69]
	v_mfma_f32_16x16x32_bf16 v[136:139], v[170:173], v[186:189], v[136:139]
	v_mfma_f32_16x16x32_bf16 v[132:135], v[178:181], v[186:189], v[132:135]
	v_mfma_f32_16x16x32_bf16 v[120:123], v[170:173], v[194:197], v[120:123]
	v_mfma_f32_16x16x32_bf16 v[116:119], v[178:181], v[194:197], v[116:119]
	v_mfma_f32_16x16x32_bf16 v[86:89], v[170:173], v[218:221], v[86:89]
	v_mfma_f32_16x16x32_bf16 v[82:85], v[178:181], v[218:221], v[82:85]
	v_mfma_f32_16x16x32_bf16 v[70:73], v[170:173], v[226:229], v[70:73]
	v_mfma_f32_16x16x32_bf16 v[66:69], v[178:181], v[226:229], v[66:69]
	s_setprio 0
	s_barrier
	s_add_i32 s44, s67, s7
	v_lshl_add_u64 v[160:161], v[160:161], 0, s[28:29]
	s_mov_b32 m0, s44
	ds_read_b128 v[182:185], v163 offset:49152
	ds_read_b128 v[186:189], v163 offset:50176
	ds_read_b128 v[190:193], v163 offset:51200
	ds_read_b128 v[194:197], v163 offset:52224
	ds_read_b128 v[214:217], v163 offset:53248
	ds_read_b128 v[218:221], v163 offset:54272
	ds_read_b128 v[222:225], v163 offset:55296
	ds_read_b128 v[226:229], v163 offset:56320
	global_load_lds_dwordx4 v[160:161], off
	s_add_i32 m0, s44, 0x2000
	s_add_u32 s42, s42, 0x40080
	v_lshl_add_u64 v[160:161], v[198:199], 0, s[28:29]
	s_addc_u32 s43, s43, 0
	s_add_i32 s44, s70, s7
	global_load_lds_dwordx4 v[160:161], off
	v_lshl_add_u64 v[160:161], s[42:43], 0, v[98:99]
	s_mov_b32 m0, s44
	s_nop 0
	global_load_lds_dwordx4 v[160:161], off
	v_lshl_add_u64 v[160:161], s[42:43], 0, v[152:153]
	s_add_i32 m0, s44, 0x2000
	s_nop 0
	global_load_lds_dwordx4 v[160:161], off
	v_lshl_add_u64 v[160:161], v[204:205], 0, s[28:29]
	s_mov_b32 m0, s16
	s_nop 0
	global_load_lds_dwordx4 v[160:161], off
	v_lshl_add_u64 v[160:161], v[206:207], 0, s[28:29]
	s_mov_b32 m0, s17
	s_nop 0
	global_load_lds_dwordx4 v[160:161], off
	s_setprio 1
	s_waitcnt vmcnt(8)
	s_waitcnt lgkmcnt(0)
	s_barrier
	v_mfma_f32_16x16x32_bf16 v[62:65], v[90:93], v[182:185], v[62:65]
	v_mfma_f32_16x16x32_bf16 v[58:61], v[100:103], v[182:185], v[58:61]
	v_mfma_f32_16x16x32_bf16 v[46:49], v[90:93], v[190:193], v[46:49]
	v_mfma_f32_16x16x32_bf16 v[42:45], v[100:103], v[190:193], v[42:45]
	v_mfma_f32_16x16x32_bf16 v[30:33], v[90:93], v[214:217], v[30:33]
	v_mfma_f32_16x16x32_bf16 v[26:29], v[100:103], v[214:217], v[26:29]
	v_mfma_f32_16x16x32_bf16 v[14:17], v[90:93], v[222:225], v[14:17]
	v_mfma_f32_16x16x32_bf16 v[10:13], v[100:103], v[222:225], v[10:13]
	v_mfma_f32_16x16x32_bf16 v[62:65], v[94:97], v[186:189], v[62:65]
	v_mfma_f32_16x16x32_bf16 v[58:61], v[108:111], v[186:189], v[58:61]
	v_mfma_f32_16x16x32_bf16 v[46:49], v[94:97], v[194:197], v[46:49]
	v_mfma_f32_16x16x32_bf16 v[42:45], v[108:111], v[194:197], v[42:45]
	v_mfma_f32_16x16x32_bf16 v[30:33], v[94:97], v[218:221], v[30:33]
	v_mfma_f32_16x16x32_bf16 v[26:29], v[108:111], v[218:221], v[26:29]
	v_mfma_f32_16x16x32_bf16 v[14:17], v[94:97], v[226:229], v[14:17]
	v_mfma_f32_16x16x32_bf16 v[10:13], v[108:111], v[226:229], v[10:13]
	s_setprio 0
	s_setprio 1
	v_mfma_f32_16x16x32_bf16 v[54:57], v[166:169], v[182:185], v[54:57]
	v_mfma_f32_16x16x32_bf16 v[50:53], v[174:177], v[182:185], v[50:53]
	v_mfma_f32_16x16x32_bf16 v[38:41], v[166:169], v[190:193], v[38:41]
	v_mfma_f32_16x16x32_bf16 v[34:37], v[174:177], v[190:193], v[34:37]
	v_mfma_f32_16x16x32_bf16 v[22:25], v[166:169], v[214:217], v[22:25]
	v_mfma_f32_16x16x32_bf16 v[18:21], v[174:177], v[214:217], v[18:21]
	v_mfma_f32_16x16x32_bf16 v[6:9], v[166:169], v[222:225], v[6:9]
	v_mfma_f32_16x16x32_bf16 v[2:5], v[174:177], v[222:225], v[2:5]
	v_mfma_f32_16x16x32_bf16 v[54:57], v[170:173], v[186:189], v[54:57]
	v_mfma_f32_16x16x32_bf16 v[50:53], v[178:181], v[186:189], v[50:53]
	v_mfma_f32_16x16x32_bf16 v[38:41], v[170:173], v[194:197], v[38:41]
	v_mfma_f32_16x16x32_bf16 v[34:37], v[178:181], v[194:197], v[34:37]
	v_mfma_f32_16x16x32_bf16 v[22:25], v[170:173], v[218:221], v[22:25]
	v_mfma_f32_16x16x32_bf16 v[18:21], v[178:181], v[218:221], v[18:21]
	v_mfma_f32_16x16x32_bf16 v[6:9], v[170:173], v[226:229], v[6:9]
	v_mfma_f32_16x16x32_bf16 v[2:5], v[178:181], v[226:229], v[2:5]
	s_setprio 0
	s_barrier
	s_add_i32 s66, s66, 2
	s_add_u32 s40, s40, 0x100
	s_addc_u32 s41, s41, 0
	s_add_u32 s64, s64, 0x100
	s_addc_u32 s65, s65, 0
	s_cmp_gt_u32 s66, 13
	s_cbranch_scc0 .LBB0_438
	s_and_b64 vcc, exec, s[22:23]
	s_cbranch_vccz .LBB0_441
	s_barrier

.LBB0_647:
	s_add_i32 s68, s42, 2
	s_add_u32 s43, s40, 0xfff80080
	s_addc_u32 s54, s41, -1
	s_add_i32 s70, 0, 0x10000
	s_cmp_eq_u32 s65, s42
	s_cselect_b32 s55, s49, s54
	s_cselect_b32 s54, s63, s43
	v_add_u32_e32 v146, s70, v149
	s_cselect_b32 s43, s51, s67
	s_cselect_b32 s42, s50, s66
	s_add_i32 s72, 0, 0x14000
	ds_read_b128 v[152:155], v146
	ds_read_b128 v[156:159], v146 offset:1024
	ds_read_b128 v[160:163], v146 offset:2048
	ds_read_b128 v[164:167], v146 offset:3072
	v_add_u32_e32 v146, s72, v149
	ds_read_b128 v[168:171], v146
	ds_read_b128 v[172:175], v146 offset:1024
	ds_read_b128 v[176:179], v146 offset:2048
	ds_read_b128 v[180:183], v146 offset:3072
	v_lshl_add_u64 v[146:147], s[40:41], 0, v[142:143]
	s_add_i32 m0, s11, 0xc000
	ds_read_b128 v[184:187], v150
	ds_read_b128 v[188:191], v150 offset:1024
	ds_read_b128 v[192:195], v150 offset:2048
	ds_read_b128 v[196:199], v150 offset:3072
	ds_read_b128 v[214:217], v150 offset:4096
	ds_read_b128 v[218:221], v150 offset:5120
	ds_read_b128 v[222:225], v150 offset:6144
	ds_read_b128 v[226:229], v150 offset:7168
	global_load_lds_dwordx4 v[146:147], off
	v_lshl_add_u64 v[146:147], s[40:41], 0, v[144:145]
	s_add_i32 m0, s11, 0xe000
	s_nop 0
	global_load_lds_dwordx4 v[146:147], off
	s_setprio 1
	s_waitcnt vmcnt(8)
	s_waitcnt lgkmcnt(0)
	s_barrier
	v_mfma_f32_16x16x32_bf16 v[128:131], v[152:155], v[184:187], v[128:131]
	v_mfma_f32_16x16x32_bf16 v[124:127], v[160:163], v[184:187], v[124:127]
	v_mfma_f32_16x16x32_bf16 v[112:115], v[152:155], v[192:195], v[112:115]
	v_mfma_f32_16x16x32_bf16 v[108:111], v[160:163], v[192:195], v[108:111]
	v_mfma_f32_16x16x32_bf16 v[94:97], v[152:155], v[214:217], v[94:97]
	v_mfma_f32_16x16x32_bf16 v[90:93], v[160:163], v[214:217], v[90:93]
	v_mfma_f32_16x16x32_bf16 v[78:81], v[152:155], v[222:225], v[78:81]
	v_mfma_f32_16x16x32_bf16 v[74:77], v[160:163], v[222:225], v[74:77]
	v_mfma_f32_16x16x32_bf16 v[128:131], v[156:159], v[188:191], v[128:131]
	v_mfma_f32_16x16x32_bf16 v[124:127], v[164:167], v[188:191], v[124:127]
	v_mfma_f32_16x16x32_bf16 v[112:115], v[156:159], v[196:199], v[112:115]
	v_mfma_f32_16x16x32_bf16 v[108:111], v[164:167], v[196:199], v[108:111]
	v_mfma_f32_16x16x32_bf16 v[94:97], v[156:159], v[218:221], v[94:97]
	v_mfma_f32_16x16x32_bf16 v[90:93], v[164:167], v[218:221], v[90:93]
	v_mfma_f32_16x16x32_bf16 v[78:81], v[156:159], v[226:229], v[78:81]
	v_mfma_f32_16x16x32_bf16 v[74:77], v[164:167], v[226:229], v[74:77]
	s_setprio 0
	s_setprio 1
	v_mfma_f32_16x16x32_bf16 v[120:123], v[168:171], v[184:187], v[120:123]
	v_mfma_f32_16x16x32_bf16 v[116:119], v[176:179], v[184:187], v[116:119]
	v_mfma_f32_16x16x32_bf16 v[104:107], v[168:171], v[192:195], v[104:107]
	v_mfma_f32_16x16x32_bf16 v[100:103], v[176:179], v[192:195], v[100:103]
	v_mfma_f32_16x16x32_bf16 v[86:89], v[168:171], v[214:217], v[86:89]
	v_mfma_f32_16x16x32_bf16 v[82:85], v[176:179], v[214:217], v[82:85]
	v_mfma_f32_16x16x32_bf16 v[70:73], v[168:171], v[222:225], v[70:73]
	v_mfma_f32_16x16x32_bf16 v[66:69], v[176:179], v[222:225], v[66:69]
	v_mfma_f32_16x16x32_bf16 v[120:123], v[172:175], v[188:191], v[120:123]
	v_mfma_f32_16x16x32_bf16 v[116:119], v[180:183], v[188:191], v[116:119]
	v_mfma_f32_16x16x32_bf16 v[104:107], v[172:175], v[196:199], v[104:107]
	v_mfma_f32_16x16x32_bf16 v[100:103], v[180:183], v[196:199], v[100:103]
	v_mfma_f32_16x16x32_bf16 v[86:89], v[172:175], v[218:221], v[86:89]
	v_mfma_f32_16x16x32_bf16 v[82:85], v[180:183], v[218:221], v[82:85]
	v_mfma_f32_16x16x32_bf16 v[70:73], v[172:175], v[226:229], v[70:73]
	v_mfma_f32_16x16x32_bf16 v[66:69], v[180:183], v[226:229], v[66:69]
	s_setprio 0
	s_barrier
	s_add_i32 s70, s70, s10
	v_lshl_add_u64 v[146:147], s[42:43], 0, v[98:99]
	s_mov_b32 m0, s70
	ds_read_b128 v[184:187], v150 offset:16384
	ds_read_b128 v[188:191], v150 offset:17408
	ds_read_b128 v[192:195], v150 offset:18432
	ds_read_b128 v[196:199], v150 offset:19456
	ds_read_b128 v[214:217], v150 offset:20480
	ds_read_b128 v[218:221], v150 offset:21504
	ds_read_b128 v[222:225], v150 offset:22528
	ds_read_b128 v[226:229], v150 offset:23552
	global_load_lds_dwordx4 v[146:147], off
	s_add_i32 m0, s70, 0x2000
	s_add_u32 s70, s42, 0x18000
	v_lshl_add_u64 v[204:205], s[42:43], 0, v[136:137]
	s_addc_u32 s71, s43, 0
	s_add_i32 s72, s72, s10
	global_load_lds_dwordx4 v[204:205], off
	v_lshl_add_u64 v[206:207], s[70:71], 0, v[98:99]
	s_mov_b32 m0, s72
	v_lshl_add_u64 v[208:209], s[54:55], 0, v[134:135]
	global_load_lds_dwordx4 v[206:207], off
	v_lshl_add_u64 v[206:207], s[70:71], 0, v[136:137]
	s_add_i32 m0, s72, 0x2000
	s_nop 0
	global_load_lds_dwordx4 v[206:207], off
	v_lshl_add_u64 v[206:207], s[54:55], 0, v[132:133]
	s_mov_b32 m0, s11
	s_nop 0
	global_load_lds_dwordx4 v[206:207], off
	s_mov_b32 m0, s12
	s_nop 0
	global_load_lds_dwordx4 v[208:209], off
	s_setprio 1
	s_waitcnt vmcnt(8)
	s_waitcnt lgkmcnt(0)
	s_barrier
	v_mfma_f32_16x16x32_bf16 v[62:65], v[152:155], v[184:187], v[62:65]
	v_mfma_f32_16x16x32_bf16 v[58:61], v[160:163], v[184:187], v[58:61]
	v_mfma_f32_16x16x32_bf16 v[46:49], v[152:155], v[192:195], v[46:49]
	v_mfma_f32_16x16x32_bf16 v[42:45], v[160:163], v[192:195], v[42:45]
	v_mfma_f32_16x16x32_bf16 v[30:33], v[152:155], v[214:217], v[30:33]
	v_mfma_f32_16x16x32_bf16 v[26:29], v[160:163], v[214:217], v[26:29]
	v_mfma_f32_16x16x32_bf16 v[14:17], v[152:155], v[222:225], v[14:17]
	v_mfma_f32_16x16x32_bf16 v[10:13], v[160:163], v[222:225], v[10:13]
	v_mfma_f32_16x16x32_bf16 v[62:65], v[156:159], v[188:191], v[62:65]
	v_mfma_f32_16x16x32_bf16 v[58:61], v[164:167], v[188:191], v[58:61]
	v_mfma_f32_16x16x32_bf16 v[46:49], v[156:159], v[196:199], v[46:49]
	v_mfma_f32_16x16x32_bf16 v[42:45], v[164:167], v[196:199], v[42:45]
	v_mfma_f32_16x16x32_bf16 v[30:33], v[156:159], v[218:221], v[30:33]
	v_mfma_f32_16x16x32_bf16 v[26:29], v[164:167], v[218:221], v[26:29]
	v_mfma_f32_16x16x32_bf16 v[14:17], v[156:159], v[226:229], v[14:17]
	v_mfma_f32_16x16x32_bf16 v[10:13], v[164:167], v[226:229], v[10:13]
	s_setprio 0
	s_setprio 1
	v_mfma_f32_16x16x32_bf16 v[54:57], v[168:171], v[184:187], v[54:57]
	v_mfma_f32_16x16x32_bf16 v[50:53], v[176:179], v[184:187], v[50:53]
	v_mfma_f32_16x16x32_bf16 v[38:41], v[168:171], v[192:195], v[38:41]
	v_mfma_f32_16x16x32_bf16 v[34:37], v[176:179], v[192:195], v[34:37]
	v_mfma_f32_16x16x32_bf16 v[22:25], v[168:171], v[214:217], v[22:25]
	v_mfma_f32_16x16x32_bf16 v[18:21], v[176:179], v[214:217], v[18:21]
	v_mfma_f32_16x16x32_bf16 v[6:9], v[168:171], v[222:225], v[6:9]
	v_mfma_f32_16x16x32_bf16 v[2:5], v[176:179], v[222:225], v[2:5]
	v_mfma_f32_16x16x32_bf16 v[54:57], v[172:175], v[188:191], v[54:57]
	v_mfma_f32_16x16x32_bf16 v[50:53], v[180:183], v[188:191], v[50:53]
	v_mfma_f32_16x16x32_bf16 v[38:41], v[172:175], v[196:199], v[38:41]
	v_mfma_f32_16x16x32_bf16 v[34:37], v[180:183], v[196:199], v[34:37]
	v_mfma_f32_16x16x32_bf16 v[22:25], v[172:175], v[218:221], v[22:25]
	v_mfma_f32_16x16x32_bf16 v[18:21], v[180:183], v[218:221], v[18:21]
	v_mfma_f32_16x16x32_bf16 v[6:9], v[172:175], v[226:229], v[6:9]
	v_mfma_f32_16x16x32_bf16 v[2:5], v[180:183], v[226:229], v[2:5]
	s_setprio 0
	s_barrier
	s_add_i32 s70, 0, 0x18000
	v_add_u32_e32 v151, s70, v149
	s_add_i32 s71, 0, 0x1c000
	ds_read_b128 v[152:155], v151
	ds_read_b128 v[156:159], v151 offset:1024
	ds_read_b128 v[160:163], v151 offset:2048
	ds_read_b128 v[164:167], v151 offset:3072
	v_add_u32_e32 v151, s71, v149
	ds_read_b128 v[168:171], v151
	ds_read_b128 v[172:175], v151 offset:1024
	ds_read_b128 v[176:179], v151 offset:2048
	ds_read_b128 v[180:183], v151 offset:3072
	s_add_u32 s54, s54, 0x80000
	s_addc_u32 s55, s55, 0
	s_mov_b32 m0, s13
	v_lshl_add_u64 v[210:211], s[54:55], 0, v[132:133]
	ds_read_b128 v[184:187], v150 offset:32768
	ds_read_b128 v[188:191], v150 offset:33792
	ds_read_b128 v[192:195], v150 offset:34816
	ds_read_b128 v[196:199], v150 offset:35840
	ds_read_b128 v[214:217], v150 offset:36864
	ds_read_b128 v[218:221], v150 offset:37888
	ds_read_b128 v[222:225], v150 offset:38912
	ds_read_b128 v[226:229], v150 offset:39936
	global_load_lds_dwordx4 v[210:211], off
	v_lshl_add_u64 v[210:211], s[54:55], 0, v[134:135]
	s_mov_b32 m0, s14
	s_nop 0
	global_load_lds_dwordx4 v[210:211], off
	s_setprio 1
	s_waitcnt vmcnt(8)
	s_waitcnt lgkmcnt(0)
	s_barrier
	v_mfma_f32_16x16x32_bf16 v[128:131], v[152:155], v[184:187], v[128:131]
	v_mfma_f32_16x16x32_bf16 v[124:127], v[160:163], v[184:187], v[124:127]
	v_mfma_f32_16x16x32_bf16 v[112:115], v[152:155], v[192:195], v[112:115]
	v_mfma_f32_16x16x32_bf16 v[108:111], v[160:163], v[192:195], v[108:111]
	v_mfma_f32_16x16x32_bf16 v[94:97], v[152:155], v[214:217], v[94:97]
	v_mfma_f32_16x16x32_bf16 v[90:93], v[160:163], v[214:217], v[90:93]
	v_mfma_f32_16x16x32_bf16 v[78:81], v[152:155], v[222:225], v[78:81]
	v_mfma_f32_16x16x32_bf16 v[74:77], v[160:163], v[222:225], v[74:77]
	v_mfma_f32_16x16x32_bf16 v[128:131], v[156:159], v[188:191], v[128:131]
	v_mfma_f32_16x16x32_bf16 v[124:127], v[164:167], v[188:191], v[124:127]
	v_mfma_f32_16x16x32_bf16 v[112:115], v[156:159], v[196:199], v[112:115]
	v_mfma_f32_16x16x32_bf16 v[108:111], v[164:167], v[196:199], v[108:111]
	v_mfma_f32_16x16x32_bf16 v[94:97], v[156:159], v[218:221], v[94:97]
	v_mfma_f32_16x16x32_bf16 v[90:93], v[164:167], v[218:221], v[90:93]
	v_mfma_f32_16x16x32_bf16 v[78:81], v[156:159], v[226:229], v[78:81]
	v_mfma_f32_16x16x32_bf16 v[74:77], v[164:167], v[226:229], v[74:77]
	s_setprio 0
	s_setprio 1
	v_mfma_f32_16x16x32_bf16 v[120:123], v[168:171], v[184:187], v[120:123]
	v_mfma_f32_16x16x32_bf16 v[116:119], v[176:179], v[184:187], v[116:119]
	v_mfma_f32_16x16x32_bf16 v[104:107], v[168:171], v[192:195], v[104:107]
	v_mfma_f32_16x16x32_bf16 v[100:103], v[176:179], v[192:195], v[100:103]
	v_mfma_f32_16x16x32_bf16 v[86:89], v[168:171], v[214:217], v[86:89]
	v_mfma_f32_16x16x32_bf16 v[82:85], v[176:179], v[214:217], v[82:85]
	v_mfma_f32_16x16x32_bf16 v[70:73], v[168:171], v[222:225], v[70:73]
	v_mfma_f32_16x16x32_bf16 v[66:69], v[176:179], v[222:225], v[66:69]
	v_mfma_f32_16x16x32_bf16 v[120:123], v[172:175], v[188:191], v[120:123]
	v_mfma_f32_16x16x32_bf16 v[116:119], v[180:183], v[188:191], v[116:119]
	v_mfma_f32_16x16x32_bf16 v[104:107], v[172:175], v[196:199], v[104:107]
	v_mfma_f32_16x16x32_bf16 v[100:103], v[180:183], v[196:199], v[100:103]
	v_mfma_f32_16x16x32_bf16 v[86:89], v[172:175], v[218:221], v[86:89]
	v_mfma_f32_16x16x32_bf16 v[82:85], v[180:183], v[218:221], v[82:85]
	v_mfma_f32_16x16x32_bf16 v[70:73], v[172:175], v[226:229], v[70:73]
	v_mfma_f32_16x16x32_bf16 v[66:69], v[180:183], v[226:229], v[66:69]
	s_setprio 0
	s_barrier
	s_add_i32 s54, s70, s10
	v_lshl_add_u64 v[146:147], v[146:147], 0, s[28:29]
	s_mov_b32 m0, s54
	ds_read_b128 v[184:187], v150 offset:49152
	ds_read_b128 v[188:191], v150 offset:50176
	ds_read_b128 v[192:195], v150 offset:51200
	ds_read_b128 v[196:199], v150 offset:52224
	ds_read_b128 v[214:217], v150 offset:53248
	ds_read_b128 v[218:221], v150 offset:54272
	ds_read_b128 v[222:225], v150 offset:55296
	ds_read_b128 v[226:229], v150 offset:56320
	global_load_lds_dwordx4 v[146:147], off
	s_add_i32 m0, s54, 0x2000
	s_add_u32 s42, s42, 0x18080
	v_lshl_add_u64 v[146:147], v[204:205], 0, s[28:29]
	s_addc_u32 s43, s43, 0
	s_add_i32 s54, s71, s10
	global_load_lds_dwordx4 v[146:147], off
	v_lshl_add_u64 v[146:147], s[42:43], 0, v[98:99]
	s_mov_b32 m0, s54
	s_nop 0
	global_load_lds_dwordx4 v[146:147], off
	v_lshl_add_u64 v[146:147], s[42:43], 0, v[136:137]
	s_add_i32 m0, s54, 0x2000
	s_nop 0
	global_load_lds_dwordx4 v[146:147], off
	v_lshl_add_u64 v[146:147], v[206:207], 0, s[28:29]
	s_mov_b32 m0, s17
	s_nop 0
	global_load_lds_dwordx4 v[146:147], off
	v_lshl_add_u64 v[146:147], v[208:209], 0, s[28:29]
	s_mov_b32 m0, s18
	s_nop 0
	global_load_lds_dwordx4 v[146:147], off
	s_setprio 1
	s_waitcnt vmcnt(8)
	s_waitcnt lgkmcnt(0)
	s_barrier
	v_mfma_f32_16x16x32_bf16 v[62:65], v[152:155], v[184:187], v[62:65]
	v_mfma_f32_16x16x32_bf16 v[58:61], v[160:163], v[184:187], v[58:61]
	v_mfma_f32_16x16x32_bf16 v[46:49], v[152:155], v[192:195], v[46:49]
	v_mfma_f32_16x16x32_bf16 v[42:45], v[160:163], v[192:195], v[42:45]
	v_mfma_f32_16x16x32_bf16 v[30:33], v[152:155], v[214:217], v[30:33]
	v_mfma_f32_16x16x32_bf16 v[26:29], v[160:163], v[214:217], v[26:29]
	v_mfma_f32_16x16x32_bf16 v[14:17], v[152:155], v[222:225], v[14:17]
	v_mfma_f32_16x16x32_bf16 v[10:13], v[160:163], v[222:225], v[10:13]
	v_mfma_f32_16x16x32_bf16 v[62:65], v[156:159], v[188:191], v[62:65]
	v_mfma_f32_16x16x32_bf16 v[58:61], v[164:167], v[188:191], v[58:61]
	v_mfma_f32_16x16x32_bf16 v[46:49], v[156:159], v[196:199], v[46:49]
	v_mfma_f32_16x16x32_bf16 v[42:45], v[164:167], v[196:199], v[42:45]
	v_mfma_f32_16x16x32_bf16 v[30:33], v[156:159], v[218:221], v[30:33]
	v_mfma_f32_16x16x32_bf16 v[26:29], v[164:167], v[218:221], v[26:29]
	v_mfma_f32_16x16x32_bf16 v[14:17], v[156:159], v[226:229], v[14:17]
	v_mfma_f32_16x16x32_bf16 v[10:13], v[164:167], v[226:229], v[10:13]
	s_setprio 0
	s_setprio 1
	v_mfma_f32_16x16x32_bf16 v[54:57], v[168:171], v[184:187], v[54:57]
	v_mfma_f32_16x16x32_bf16 v[50:53], v[176:179], v[184:187], v[50:53]
	v_mfma_f32_16x16x32_bf16 v[38:41], v[168:171], v[192:195], v[38:41]
	v_mfma_f32_16x16x32_bf16 v[34:37], v[176:179], v[192:195], v[34:37]
	v_mfma_f32_16x16x32_bf16 v[22:25], v[168:171], v[214:217], v[22:25]
	v_mfma_f32_16x16x32_bf16 v[18:21], v[176:179], v[214:217], v[18:21]
	v_mfma_f32_16x16x32_bf16 v[6:9], v[168:171], v[222:225], v[6:9]
	v_mfma_f32_16x16x32_bf16 v[2:5], v[176:179], v[222:225], v[2:5]
	v_mfma_f32_16x16x32_bf16 v[54:57], v[172:175], v[188:191], v[54:57]
	v_mfma_f32_16x16x32_bf16 v[50:53], v[180:183], v[188:191], v[50:53]
	v_mfma_f32_16x16x32_bf16 v[38:41], v[172:175], v[196:199], v[38:41]
	v_mfma_f32_16x16x32_bf16 v[34:37], v[180:183], v[196:199], v[34:37]
	v_mfma_f32_16x16x32_bf16 v[22:25], v[172:175], v[218:221], v[22:25]
	v_mfma_f32_16x16x32_bf16 v[18:21], v[180:183], v[218:221], v[18:21]
	v_mfma_f32_16x16x32_bf16 v[6:9], v[172:175], v[226:229], v[6:9]
	v_mfma_f32_16x16x32_bf16 v[2:5], v[180:183], v[226:229], v[2:5]
	s_setprio 0
	s_barrier
	s_add_u32 s40, s40, 0x100
	s_addc_u32 s41, s41, 0
	s_add_u32 s66, s66, 0x100
	s_addc_u32 s67, s67, 0
	s_cmp_ge_i32 s68, s62
	s_mov_b32 s42, s68
	s_cbranch_scc0 .LBB0_647
	s_and_b64 vcc, exec, s[44:45]
	s_cbranch_vccz .LBB0_650
	s_barrier

.LBB0_893:
	s_add_u32 s50, s48, 0xfffe0080
	s_addc_u32 s51, s49, -1
	s_add_i32 s57, 0, 0x10000
	s_cmp_eq_u32 s56, 4
	s_cselect_b32 s53, s19, s51
	s_cselect_b32 s52, s33, s50
	v_add_u32_e32 v98, s57, v144
	s_cselect_b32 s51, s37, s55
	s_cselect_b32 s50, s39, s54
	s_add_i32 s60, 0, 0x14000
	ds_read_b128 v[146:149], v98
	ds_read_b128 v[150:153], v98 offset:1024
	ds_read_b128 v[154:157], v98 offset:2048
	ds_read_b128 v[158:161], v98 offset:3072
	v_add_u32_e32 v98, s60, v144
	ds_read_b128 v[162:165], v98
	ds_read_b128 v[166:169], v98 offset:1024
	ds_read_b128 v[170:173], v98 offset:2048
	ds_read_b128 v[174:177], v98 offset:3072
	v_lshl_add_u64 v[198:199], s[48:49], 0, v[140:141]
	s_add_i32 m0, s4, 0xc000
	ds_read_b128 v[178:181], v145
	ds_read_b128 v[182:185], v145 offset:1024
	ds_read_b128 v[186:189], v145 offset:2048
	ds_read_b128 v[190:193], v145 offset:3072
	ds_read_b128 v[194:197], v145 offset:4096
	ds_read_b128 v[204:207], v145 offset:5120
	ds_read_b128 v[208:211], v145 offset:6144
	ds_read_b128 v[214:217], v145 offset:7168
	global_load_lds_dwordx4 v[198:199], off
	v_lshl_add_u64 v[198:199], s[48:49], 0, v[142:143]
	s_add_i32 m0, s4, 0xe000
	s_nop 0
	global_load_lds_dwordx4 v[198:199], off
	s_setprio 1
	s_waitcnt vmcnt(8)
	s_waitcnt lgkmcnt(0)
	s_barrier
	v_mfma_f32_16x16x32_bf16 v[128:131], v[146:149], v[178:181], v[128:131]
	v_mfma_f32_16x16x32_bf16 v[124:127], v[154:157], v[178:181], v[124:127]
	v_mfma_f32_16x16x32_bf16 v[112:115], v[146:149], v[186:189], v[112:115]
	v_mfma_f32_16x16x32_bf16 v[108:111], v[154:157], v[186:189], v[108:111]
	v_mfma_f32_16x16x32_bf16 v[94:97], v[146:149], v[194:197], v[94:97]
	v_mfma_f32_16x16x32_bf16 v[90:93], v[154:157], v[194:197], v[90:93]
	v_mfma_f32_16x16x32_bf16 v[78:81], v[146:149], v[208:211], v[78:81]
	v_mfma_f32_16x16x32_bf16 v[74:77], v[154:157], v[208:211], v[74:77]
	v_mfma_f32_16x16x32_bf16 v[128:131], v[150:153], v[182:185], v[128:131]
	v_mfma_f32_16x16x32_bf16 v[124:127], v[158:161], v[182:185], v[124:127]
	v_mfma_f32_16x16x32_bf16 v[112:115], v[150:153], v[190:193], v[112:115]
	v_mfma_f32_16x16x32_bf16 v[108:111], v[158:161], v[190:193], v[108:111]
	v_mfma_f32_16x16x32_bf16 v[94:97], v[150:153], v[204:207], v[94:97]
	v_mfma_f32_16x16x32_bf16 v[90:93], v[158:161], v[204:207], v[90:93]
	v_mfma_f32_16x16x32_bf16 v[78:81], v[150:153], v[214:217], v[78:81]
	v_mfma_f32_16x16x32_bf16 v[74:77], v[158:161], v[214:217], v[74:77]
	s_setprio 0
	s_setprio 1
	v_mfma_f32_16x16x32_bf16 v[120:123], v[162:165], v[178:181], v[120:123]
	v_mfma_f32_16x16x32_bf16 v[116:119], v[170:173], v[178:181], v[116:119]
	v_mfma_f32_16x16x32_bf16 v[104:107], v[162:165], v[186:189], v[104:107]
	v_mfma_f32_16x16x32_bf16 v[100:103], v[170:173], v[186:189], v[100:103]
	v_mfma_f32_16x16x32_bf16 v[86:89], v[162:165], v[194:197], v[86:89]
	v_mfma_f32_16x16x32_bf16 v[82:85], v[170:173], v[194:197], v[82:85]
	v_mfma_f32_16x16x32_bf16 v[70:73], v[162:165], v[208:211], v[70:73]
	v_mfma_f32_16x16x32_bf16 v[66:69], v[170:173], v[208:211], v[66:69]
	v_mfma_f32_16x16x32_bf16 v[120:123], v[166:169], v[182:185], v[120:123]
	v_mfma_f32_16x16x32_bf16 v[116:119], v[174:177], v[182:185], v[116:119]
	v_mfma_f32_16x16x32_bf16 v[104:107], v[166:169], v[190:193], v[104:107]
	v_mfma_f32_16x16x32_bf16 v[100:103], v[174:177], v[190:193], v[100:103]
	v_mfma_f32_16x16x32_bf16 v[86:89], v[166:169], v[204:207], v[86:89]
	v_mfma_f32_16x16x32_bf16 v[82:85], v[174:177], v[204:207], v[82:85]
	v_mfma_f32_16x16x32_bf16 v[70:73], v[166:169], v[214:217], v[70:73]
	v_mfma_f32_16x16x32_bf16 v[66:69], v[174:177], v[214:217], v[66:69]
	s_setprio 0
	s_barrier
	s_add_i32 s57, s57, s2
	v_lshl_add_u64 v[198:199], s[50:51], 0, v[136:137]
	s_mov_b32 m0, s57
	ds_read_b128 v[178:181], v145 offset:16384
	ds_read_b128 v[182:185], v145 offset:17408
	ds_read_b128 v[186:189], v145 offset:18432
	ds_read_b128 v[190:193], v145 offset:19456
	ds_read_b128 v[194:197], v145 offset:20480
	ds_read_b128 v[204:207], v145 offset:21504
	ds_read_b128 v[208:211], v145 offset:22528
	ds_read_b128 v[214:217], v145 offset:23552
	global_load_lds_dwordx4 v[198:199], off
	s_add_i32 m0, s57, 0x2000
	s_add_u32 s58, s50, 0x20000
	v_lshl_add_u64 v[218:219], s[50:51], 0, v[132:133]
	s_addc_u32 s59, s51, 0
	s_add_i32 s57, s60, s2
	global_load_lds_dwordx4 v[218:219], off
	v_lshl_add_u64 v[220:221], s[58:59], 0, v[136:137]
	s_mov_b32 m0, s57
	v_lshl_add_u64 v[222:223], s[52:53], 0, v[134:135]
	global_load_lds_dwordx4 v[220:221], off
	v_lshl_add_u64 v[220:221], s[58:59], 0, v[132:133]
	s_add_i32 m0, s57, 0x2000
	s_nop 0
	global_load_lds_dwordx4 v[220:221], off
	v_lshl_add_u64 v[220:221], s[52:53], 0, v[138:139]
	s_mov_b32 m0, s4
	s_nop 0
	global_load_lds_dwordx4 v[220:221], off
	s_mov_b32 m0, s7
	s_nop 0
	global_load_lds_dwordx4 v[222:223], off
	s_setprio 1
	s_waitcnt vmcnt(8)
	s_waitcnt lgkmcnt(0)
	s_barrier
	v_mfma_f32_16x16x32_bf16 v[62:65], v[146:149], v[178:181], v[62:65]
	v_mfma_f32_16x16x32_bf16 v[58:61], v[154:157], v[178:181], v[58:61]
	v_mfma_f32_16x16x32_bf16 v[46:49], v[146:149], v[186:189], v[46:49]
	v_mfma_f32_16x16x32_bf16 v[42:45], v[154:157], v[186:189], v[42:45]
	v_mfma_f32_16x16x32_bf16 v[30:33], v[146:149], v[194:197], v[30:33]
	v_mfma_f32_16x16x32_bf16 v[26:29], v[154:157], v[194:197], v[26:29]
	v_mfma_f32_16x16x32_bf16 v[14:17], v[146:149], v[208:211], v[14:17]
	v_mfma_f32_16x16x32_bf16 v[10:13], v[154:157], v[208:211], v[10:13]
	v_mfma_f32_16x16x32_bf16 v[62:65], v[150:153], v[182:185], v[62:65]
	v_mfma_f32_16x16x32_bf16 v[58:61], v[158:161], v[182:185], v[58:61]
	v_mfma_f32_16x16x32_bf16 v[46:49], v[150:153], v[190:193], v[46:49]
	v_mfma_f32_16x16x32_bf16 v[42:45], v[158:161], v[190:193], v[42:45]
	v_mfma_f32_16x16x32_bf16 v[30:33], v[150:153], v[204:207], v[30:33]
	v_mfma_f32_16x16x32_bf16 v[26:29], v[158:161], v[204:207], v[26:29]
	v_mfma_f32_16x16x32_bf16 v[14:17], v[150:153], v[214:217], v[14:17]
	v_mfma_f32_16x16x32_bf16 v[10:13], v[158:161], v[214:217], v[10:13]
	s_setprio 0
	s_setprio 1
	v_mfma_f32_16x16x32_bf16 v[54:57], v[162:165], v[178:181], v[54:57]
	v_mfma_f32_16x16x32_bf16 v[50:53], v[170:173], v[178:181], v[50:53]
	v_mfma_f32_16x16x32_bf16 v[38:41], v[162:165], v[186:189], v[38:41]
	v_mfma_f32_16x16x32_bf16 v[34:37], v[170:173], v[186:189], v[34:37]
	v_mfma_f32_16x16x32_bf16 v[22:25], v[162:165], v[194:197], v[22:25]
	v_mfma_f32_16x16x32_bf16 v[18:21], v[170:173], v[194:197], v[18:21]
	v_mfma_f32_16x16x32_bf16 v[6:9], v[162:165], v[208:211], v[6:9]
	v_mfma_f32_16x16x32_bf16 v[2:5], v[170:173], v[208:211], v[2:5]
	v_mfma_f32_16x16x32_bf16 v[54:57], v[166:169], v[182:185], v[54:57]
	v_mfma_f32_16x16x32_bf16 v[50:53], v[174:177], v[182:185], v[50:53]
	v_mfma_f32_16x16x32_bf16 v[38:41], v[166:169], v[190:193], v[38:41]
	v_mfma_f32_16x16x32_bf16 v[34:37], v[174:177], v[190:193], v[34:37]
	v_mfma_f32_16x16x32_bf16 v[22:25], v[166:169], v[204:207], v[22:25]
	v_mfma_f32_16x16x32_bf16 v[18:21], v[174:177], v[204:207], v[18:21]
	v_mfma_f32_16x16x32_bf16 v[6:9], v[166:169], v[214:217], v[6:9]
	v_mfma_f32_16x16x32_bf16 v[2:5], v[174:177], v[214:217], v[2:5]
	s_setprio 0
	s_barrier
	s_add_i32 s57, 0, 0x18000
	v_add_u32_e32 v98, s57, v144
	s_add_i32 s58, 0, 0x1c000
	ds_read_b128 v[146:149], v98
	ds_read_b128 v[150:153], v98 offset:1024
	ds_read_b128 v[154:157], v98 offset:2048
	ds_read_b128 v[158:161], v98 offset:3072
	v_add_u32_e32 v98, s58, v144
	ds_read_b128 v[162:165], v98
	ds_read_b128 v[166:169], v98 offset:1024
	ds_read_b128 v[170:173], v98 offset:2048
	ds_read_b128 v[174:177], v98 offset:3072
	s_add_u32 s52, s52, 0x20000
	s_addc_u32 s53, s53, 0
	s_mov_b32 m0, s8
	v_lshl_add_u64 v[224:225], s[52:53], 0, v[138:139]
	ds_read_b128 v[178:181], v145 offset:32768
	ds_read_b128 v[182:185], v145 offset:33792
	ds_read_b128 v[186:189], v145 offset:34816
	ds_read_b128 v[190:193], v145 offset:35840
	ds_read_b128 v[194:197], v145 offset:36864
	ds_read_b128 v[204:207], v145 offset:37888
	ds_read_b128 v[208:211], v145 offset:38912
	ds_read_b128 v[214:217], v145 offset:39936
	global_load_lds_dwordx4 v[224:225], off
	v_lshl_add_u64 v[224:225], s[52:53], 0, v[134:135]
	s_mov_b32 m0, s9
	s_nop 0
	global_load_lds_dwordx4 v[224:225], off
	s_setprio 1
	s_waitcnt vmcnt(8)
	s_waitcnt lgkmcnt(0)
	s_barrier
	v_mfma_f32_16x16x32_bf16 v[128:131], v[146:149], v[178:181], v[128:131]
	v_mfma_f32_16x16x32_bf16 v[124:127], v[154:157], v[178:181], v[124:127]
	v_mfma_f32_16x16x32_bf16 v[112:115], v[146:149], v[186:189], v[112:115]
	v_mfma_f32_16x16x32_bf16 v[108:111], v[154:157], v[186:189], v[108:111]
	v_mfma_f32_16x16x32_bf16 v[94:97], v[146:149], v[194:197], v[94:97]
	v_mfma_f32_16x16x32_bf16 v[90:93], v[154:157], v[194:197], v[90:93]
	v_mfma_f32_16x16x32_bf16 v[78:81], v[146:149], v[208:211], v[78:81]
	v_mfma_f32_16x16x32_bf16 v[74:77], v[154:157], v[208:211], v[74:77]
	v_mfma_f32_16x16x32_bf16 v[128:131], v[150:153], v[182:185], v[128:131]
	v_mfma_f32_16x16x32_bf16 v[124:127], v[158:161], v[182:185], v[124:127]
	v_mfma_f32_16x16x32_bf16 v[112:115], v[150:153], v[190:193], v[112:115]
	v_mfma_f32_16x16x32_bf16 v[108:111], v[158:161], v[190:193], v[108:111]
	v_mfma_f32_16x16x32_bf16 v[94:97], v[150:153], v[204:207], v[94:97]
	v_mfma_f32_16x16x32_bf16 v[90:93], v[158:161], v[204:207], v[90:93]
	v_mfma_f32_16x16x32_bf16 v[78:81], v[150:153], v[214:217], v[78:81]
	v_mfma_f32_16x16x32_bf16 v[74:77], v[158:161], v[214:217], v[74:77]
	s_setprio 0
	s_setprio 1
	v_mfma_f32_16x16x32_bf16 v[120:123], v[162:165], v[178:181], v[120:123]
	v_mfma_f32_16x16x32_bf16 v[116:119], v[170:173], v[178:181], v[116:119]
	v_mfma_f32_16x16x32_bf16 v[104:107], v[162:165], v[186:189], v[104:107]
	v_mfma_f32_16x16x32_bf16 v[100:103], v[170:173], v[186:189], v[100:103]
	v_mfma_f32_16x16x32_bf16 v[86:89], v[162:165], v[194:197], v[86:89]
	v_mfma_f32_16x16x32_bf16 v[82:85], v[170:173], v[194:197], v[82:85]
	v_mfma_f32_16x16x32_bf16 v[70:73], v[162:165], v[208:211], v[70:73]
	v_mfma_f32_16x16x32_bf16 v[66:69], v[170:173], v[208:211], v[66:69]
	v_mfma_f32_16x16x32_bf16 v[120:123], v[166:169], v[182:185], v[120:123]
	v_mfma_f32_16x16x32_bf16 v[116:119], v[174:177], v[182:185], v[116:119]
	v_mfma_f32_16x16x32_bf16 v[104:107], v[166:169], v[190:193], v[104:107]
	v_mfma_f32_16x16x32_bf16 v[100:103], v[174:177], v[190:193], v[100:103]
	v_mfma_f32_16x16x32_bf16 v[86:89], v[166:169], v[204:207], v[86:89]
	v_mfma_f32_16x16x32_bf16 v[82:85], v[174:177], v[204:207], v[82:85]
	v_mfma_f32_16x16x32_bf16 v[70:73], v[166:169], v[214:217], v[70:73]
	v_mfma_f32_16x16x32_bf16 v[66:69], v[174:177], v[214:217], v[66:69]
	s_setprio 0
	s_barrier
	s_add_i32 s52, s57, s2
	v_lshl_add_u64 v[198:199], v[198:199], 0, s[28:29]
	s_mov_b32 m0, s52
	ds_read_b128 v[178:181], v145 offset:49152
	ds_read_b128 v[182:185], v145 offset:50176
	ds_read_b128 v[186:189], v145 offset:51200
	ds_read_b128 v[190:193], v145 offset:52224
	ds_read_b128 v[194:197], v145 offset:53248
	ds_read_b128 v[204:207], v145 offset:54272
	ds_read_b128 v[208:211], v145 offset:55296
	ds_read_b128 v[214:217], v145 offset:56320
	global_load_lds_dwordx4 v[198:199], off
	s_add_i32 m0, s52, 0x2000
	s_add_u32 s50, s50, 0x20080
	v_lshl_add_u64 v[198:199], v[218:219], 0, s[28:29]
	s_addc_u32 s51, s51, 0
	s_add_i32 s52, s58, s2
	global_load_lds_dwordx4 v[198:199], off
	v_lshl_add_u64 v[198:199], s[50:51], 0, v[136:137]
	s_mov_b32 m0, s52
	s_nop 0
	global_load_lds_dwordx4 v[198:199], off
	v_lshl_add_u64 v[198:199], s[50:51], 0, v[132:133]
	s_add_i32 m0, s52, 0x2000
	s_nop 0
	global_load_lds_dwordx4 v[198:199], off
	v_lshl_add_u64 v[198:199], v[220:221], 0, s[28:29]
	s_mov_b32 m0, s12
	s_nop 0
	global_load_lds_dwordx4 v[198:199], off
	v_lshl_add_u64 v[198:199], v[222:223], 0, s[28:29]
	s_mov_b32 m0, s13
	s_nop 0
	global_load_lds_dwordx4 v[198:199], off
	s_setprio 1
	s_waitcnt vmcnt(8)
	s_waitcnt lgkmcnt(0)
	s_barrier
	v_mfma_f32_16x16x32_bf16 v[62:65], v[146:149], v[178:181], v[62:65]
	v_mfma_f32_16x16x32_bf16 v[58:61], v[154:157], v[178:181], v[58:61]
	v_mfma_f32_16x16x32_bf16 v[46:49], v[146:149], v[186:189], v[46:49]
	v_mfma_f32_16x16x32_bf16 v[42:45], v[154:157], v[186:189], v[42:45]
	v_mfma_f32_16x16x32_bf16 v[30:33], v[146:149], v[194:197], v[30:33]
	v_mfma_f32_16x16x32_bf16 v[26:29], v[154:157], v[194:197], v[26:29]
	v_mfma_f32_16x16x32_bf16 v[14:17], v[146:149], v[208:211], v[14:17]
	v_mfma_f32_16x16x32_bf16 v[10:13], v[154:157], v[208:211], v[10:13]
	v_mfma_f32_16x16x32_bf16 v[62:65], v[150:153], v[182:185], v[62:65]
	v_mfma_f32_16x16x32_bf16 v[58:61], v[158:161], v[182:185], v[58:61]
	v_mfma_f32_16x16x32_bf16 v[46:49], v[150:153], v[190:193], v[46:49]
	v_mfma_f32_16x16x32_bf16 v[42:45], v[158:161], v[190:193], v[42:45]
	v_mfma_f32_16x16x32_bf16 v[30:33], v[150:153], v[204:207], v[30:33]
	v_mfma_f32_16x16x32_bf16 v[26:29], v[158:161], v[204:207], v[26:29]
	v_mfma_f32_16x16x32_bf16 v[14:17], v[150:153], v[214:217], v[14:17]
	v_mfma_f32_16x16x32_bf16 v[10:13], v[158:161], v[214:217], v[10:13]
	s_setprio 0
	s_setprio 1
	v_mfma_f32_16x16x32_bf16 v[54:57], v[162:165], v[178:181], v[54:57]
	v_mfma_f32_16x16x32_bf16 v[50:53], v[170:173], v[178:181], v[50:53]
	v_mfma_f32_16x16x32_bf16 v[38:41], v[162:165], v[186:189], v[38:41]
	v_mfma_f32_16x16x32_bf16 v[34:37], v[170:173], v[186:189], v[34:37]
	v_mfma_f32_16x16x32_bf16 v[22:25], v[162:165], v[194:197], v[22:25]
	v_mfma_f32_16x16x32_bf16 v[18:21], v[170:173], v[194:197], v[18:21]
	v_mfma_f32_16x16x32_bf16 v[6:9], v[162:165], v[208:211], v[6:9]
	v_mfma_f32_16x16x32_bf16 v[2:5], v[170:173], v[208:211], v[2:5]
	v_mfma_f32_16x16x32_bf16 v[54:57], v[166:169], v[182:185], v[54:57]
	v_mfma_f32_16x16x32_bf16 v[50:53], v[174:177], v[182:185], v[50:53]
	v_mfma_f32_16x16x32_bf16 v[38:41], v[166:169], v[190:193], v[38:41]
	v_mfma_f32_16x16x32_bf16 v[34:37], v[174:177], v[190:193], v[34:37]
	v_mfma_f32_16x16x32_bf16 v[22:25], v[166:169], v[204:207], v[22:25]
	v_mfma_f32_16x16x32_bf16 v[18:21], v[174:177], v[204:207], v[18:21]
	v_mfma_f32_16x16x32_bf16 v[6:9], v[166:169], v[214:217], v[6:9]
	v_mfma_f32_16x16x32_bf16 v[2:5], v[174:177], v[214:217], v[2:5]
	s_setprio 0
	s_barrier
	s_add_i32 s56, s56, 2
	s_add_u32 s48, s48, 0x100
	s_addc_u32 s49, s49, 0
	s_add_u32 s54, s54, 0x100
	s_addc_u32 s55, s55, 0
	s_cmp_gt_u32 s56, 5
	s_cbranch_scc0 .LBB0_893
	s_and_b64 vcc, exec, s[22:23]
	s_cbranch_vccz .LBB0_896
	s_barrier

.LBB0_1072:
	s_add_u32 s60, s56, s58
	s_addc_u32 s61, s57, s59
	s_add_u32 s60, s60, 0x100
	s_addc_u32 s61, s61, 0
	s_add_u32 s71, s66, s58
	s_addc_u32 s72, s67, s59
	s_add_i32 s73, 0, 0x10000
	s_cmpk_eq_i32 s58, 0x700
	s_cselect_b32 s63, s45, s61
	s_cselect_b32 s62, s51, s60
	v_add_u32_e32 v98, s73, v214
	s_cselect_b32 s61, s49, s72
	s_cselect_b32 s60, s65, s71
	s_add_i32 s71, 0, 0x14000
	ds_read_b128 v[138:141], v98
	ds_read_b128 v[142:145], v98 offset:1024
	ds_read_b128 v[146:149], v98 offset:2048
	ds_read_b128 v[150:153], v98 offset:3072
	v_add_u32_e32 v98, s71, v214
	ds_read_b128 v[154:157], v98
	ds_read_b128 v[158:161], v98 offset:1024
	ds_read_b128 v[162:165], v98 offset:2048
	ds_read_b128 v[166:169], v98 offset:3072
	v_lshl_add_u64 v[100:101], v[134:135], 0, s[58:59]
	s_add_i32 m0, s9, 0xc000
	ds_read_b128 v[170:173], v218
	ds_read_b128 v[186:189], v218 offset:1024
	ds_read_b128 v[190:193], v218 offset:2048
	ds_read_b128 v[194:197], v218 offset:3072
	ds_read_b128 v[204:207], v218 offset:4096
	ds_read_b128 v[208:211], v218 offset:5120
	ds_read_b128 v[220:223], v218 offset:6144
	ds_read_b128 v[224:227], v218 offset:7168
	global_load_lds_dwordx4 v[100:101], off
	v_lshl_add_u64 v[100:101], v[136:137], 0, s[58:59]
	s_add_i32 m0, s9, 0xe000
	s_nop 0
	global_load_lds_dwordx4 v[100:101], off
	s_setprio 1
	s_waitcnt vmcnt(8)
	s_waitcnt lgkmcnt(0)
	s_barrier
	v_mfma_f32_16x16x32_bf16 v[130:133], v[138:141], v[170:173], v[130:133]
	v_mfma_f32_16x16x32_bf16 v[126:129], v[146:149], v[170:173], v[126:129]
	v_mfma_f32_16x16x32_bf16 v[122:125], v[138:141], v[190:193], v[122:125]
	v_mfma_f32_16x16x32_bf16 v[118:121], v[146:149], v[190:193], v[118:121]
	v_mfma_f32_16x16x32_bf16 v[114:117], v[138:141], v[204:207], v[114:117]
	v_mfma_f32_16x16x32_bf16 v[110:113], v[146:149], v[204:207], v[110:113]
	v_mfma_f32_16x16x32_bf16 v[106:109], v[138:141], v[220:223], v[106:109]
	v_mfma_f32_16x16x32_bf16 v[100:103], v[146:149], v[220:223], v[102:105]
	v_mfma_f32_16x16x32_bf16 v[130:133], v[142:145], v[186:189], v[130:133]
	v_mfma_f32_16x16x32_bf16 v[126:129], v[150:153], v[186:189], v[126:129]
	v_mfma_f32_16x16x32_bf16 v[122:125], v[142:145], v[194:197], v[122:125]
	v_mfma_f32_16x16x32_bf16 v[118:121], v[150:153], v[194:197], v[118:121]
	v_mfma_f32_16x16x32_bf16 v[114:117], v[142:145], v[208:211], v[114:117]
	v_mfma_f32_16x16x32_bf16 v[110:113], v[150:153], v[208:211], v[110:113]
	v_mfma_f32_16x16x32_bf16 v[106:109], v[142:145], v[224:227], v[106:109]
	v_mfma_f32_16x16x32_bf16 v[100:103], v[150:153], v[224:227], v[100:103]
	s_setprio 0
	s_setprio 1
	v_mfma_f32_16x16x32_bf16 v[62:65], v[154:157], v[170:173], v[62:65]
	v_mfma_f32_16x16x32_bf16 v[58:61], v[162:165], v[170:173], v[58:61]
	v_mfma_f32_16x16x32_bf16 v[54:57], v[154:157], v[190:193], v[54:57]
	v_mfma_f32_16x16x32_bf16 v[50:53], v[162:165], v[190:193], v[50:53]
	v_mfma_f32_16x16x32_bf16 v[46:49], v[154:157], v[204:207], v[46:49]
	v_mfma_f32_16x16x32_bf16 v[42:45], v[162:165], v[204:207], v[42:45]
	v_mfma_f32_16x16x32_bf16 v[38:41], v[154:157], v[220:223], v[38:41]
	v_mfma_f32_16x16x32_bf16 v[34:37], v[162:165], v[220:223], v[34:37]
	v_mfma_f32_16x16x32_bf16 v[62:65], v[158:161], v[186:189], v[62:65]
	v_mfma_f32_16x16x32_bf16 v[58:61], v[166:169], v[186:189], v[58:61]
	v_mfma_f32_16x16x32_bf16 v[54:57], v[158:161], v[194:197], v[54:57]
	v_mfma_f32_16x16x32_bf16 v[50:53], v[166:169], v[194:197], v[50:53]
	v_mfma_f32_16x16x32_bf16 v[46:49], v[158:161], v[208:211], v[46:49]
	v_mfma_f32_16x16x32_bf16 v[42:45], v[166:169], v[208:211], v[42:45]
	v_mfma_f32_16x16x32_bf16 v[38:41], v[158:161], v[224:227], v[38:41]
	v_mfma_f32_16x16x32_bf16 v[34:37], v[166:169], v[224:227], v[34:37]
	s_setprio 0
	s_barrier
	s_add_i32 s72, s73, s4
	v_lshl_add_u64 v[198:199], s[60:61], 0, v[176:177]
	s_mov_b32 m0, s72
	ds_read_b128 v[170:173], v218 offset:16384
	ds_read_b128 v[186:189], v218 offset:17408
	ds_read_b128 v[190:193], v218 offset:18432
	ds_read_b128 v[194:197], v218 offset:19456
	ds_read_b128 v[204:207], v218 offset:20480
	ds_read_b128 v[208:211], v218 offset:21504
	ds_read_b128 v[220:223], v218 offset:22528
	ds_read_b128 v[224:227], v218 offset:23552
	global_load_lds_dwordx4 v[198:199], off
	s_add_i32 m0, s72, 0x2000
	s_add_u32 s72, s60, 0x40000
	v_lshl_add_u64 v[228:229], s[60:61], 0, v[180:181]
	s_addc_u32 s73, s61, 0
	s_add_i32 s71, s71, s4
	global_load_lds_dwordx4 v[228:229], off
	v_lshl_add_u64 v[104:105], s[72:73], 0, v[176:177]
	s_mov_b32 m0, s71
	v_lshl_add_u64 v[230:231], s[62:63], 0, v[174:175]
	global_load_lds_dwordx4 v[104:105], off
	v_lshl_add_u64 v[104:105], s[72:73], 0, v[180:181]
	s_add_i32 m0, s71, 0x2000
	v_lshl_add_u64 v[232:233], s[62:63], 0, v[178:179]
	global_load_lds_dwordx4 v[104:105], off
	s_mov_b32 m0, s9
	s_nop 0
	global_load_lds_dwordx4 v[230:231], off
	s_mov_b32 m0, s10
	s_nop 0
	global_load_lds_dwordx4 v[232:233], off
	s_setprio 1
	s_waitcnt vmcnt(8)
	s_waitcnt lgkmcnt(0)
	s_barrier
	v_mfma_f32_16x16x32_bf16 v[94:97], v[138:141], v[170:173], v[94:97]
	v_mfma_f32_16x16x32_bf16 v[90:93], v[146:149], v[170:173], v[90:93]
	v_mfma_f32_16x16x32_bf16 v[86:89], v[138:141], v[190:193], v[86:89]
	v_mfma_f32_16x16x32_bf16 v[82:85], v[146:149], v[190:193], v[82:85]
	v_mfma_f32_16x16x32_bf16 v[78:81], v[138:141], v[204:207], v[78:81]
	v_mfma_f32_16x16x32_bf16 v[74:77], v[146:149], v[204:207], v[74:77]
	v_mfma_f32_16x16x32_bf16 v[70:73], v[138:141], v[220:223], v[70:73]
	v_mfma_f32_16x16x32_bf16 v[66:69], v[146:149], v[220:223], v[66:69]
	v_mfma_f32_16x16x32_bf16 v[94:97], v[142:145], v[186:189], v[94:97]
	v_mfma_f32_16x16x32_bf16 v[90:93], v[150:153], v[186:189], v[90:93]
	v_mfma_f32_16x16x32_bf16 v[86:89], v[142:145], v[194:197], v[86:89]
	v_mfma_f32_16x16x32_bf16 v[82:85], v[150:153], v[194:197], v[82:85]
	v_mfma_f32_16x16x32_bf16 v[78:81], v[142:145], v[208:211], v[78:81]
	v_mfma_f32_16x16x32_bf16 v[74:77], v[150:153], v[208:211], v[74:77]
	v_mfma_f32_16x16x32_bf16 v[70:73], v[142:145], v[224:227], v[70:73]
	v_mfma_f32_16x16x32_bf16 v[66:69], v[150:153], v[224:227], v[66:69]
	s_setprio 0
	s_setprio 1
	v_mfma_f32_16x16x32_bf16 v[30:33], v[154:157], v[170:173], v[30:33]
	v_mfma_f32_16x16x32_bf16 v[26:29], v[162:165], v[170:173], v[26:29]
	v_mfma_f32_16x16x32_bf16 v[22:25], v[154:157], v[190:193], v[22:25]
	v_mfma_f32_16x16x32_bf16 v[18:21], v[162:165], v[190:193], v[18:21]
	v_mfma_f32_16x16x32_bf16 v[14:17], v[154:157], v[204:207], v[14:17]
	v_mfma_f32_16x16x32_bf16 v[10:13], v[162:165], v[204:207], v[10:13]
	v_mfma_f32_16x16x32_bf16 v[6:9], v[154:157], v[220:223], v[6:9]
	v_mfma_f32_16x16x32_bf16 v[2:5], v[162:165], v[220:223], v[2:5]
	v_mfma_f32_16x16x32_bf16 v[30:33], v[158:161], v[186:189], v[30:33]
	v_mfma_f32_16x16x32_bf16 v[26:29], v[166:169], v[186:189], v[26:29]
	v_mfma_f32_16x16x32_bf16 v[22:25], v[158:161], v[194:197], v[22:25]
	v_mfma_f32_16x16x32_bf16 v[18:21], v[166:169], v[194:197], v[18:21]
	v_mfma_f32_16x16x32_bf16 v[14:17], v[158:161], v[208:211], v[14:17]
	v_mfma_f32_16x16x32_bf16 v[10:13], v[166:169], v[208:211], v[10:13]
	v_mfma_f32_16x16x32_bf16 v[6:9], v[158:161], v[224:227], v[6:9]
	v_mfma_f32_16x16x32_bf16 v[2:5], v[166:169], v[224:227], v[2:5]
	s_setprio 0
	s_barrier
	s_add_i32 s71, 0, 0x18000
	v_add_u32_e32 v98, s71, v214
	s_add_i32 s72, 0, 0x1c000
	ds_read_b128 v[138:141], v98
	ds_read_b128 v[142:145], v98 offset:1024
	ds_read_b128 v[146:149], v98 offset:2048
	ds_read_b128 v[150:153], v98 offset:3072
	v_add_u32_e32 v98, s72, v214
	ds_read_b128 v[154:157], v98
	ds_read_b128 v[158:161], v98 offset:1024
	ds_read_b128 v[162:165], v98 offset:2048
	ds_read_b128 v[166:169], v98 offset:3072
	s_add_u32 s62, s62, 0x40000
	s_addc_u32 s63, s63, 0
	s_mov_b32 m0, s11
	v_lshl_add_u64 v[104:105], s[62:63], 0, v[174:175]
	ds_read_b128 v[170:173], v218 offset:32768
	ds_read_b128 v[186:189], v218 offset:33792
	ds_read_b128 v[190:193], v218 offset:34816
	ds_read_b128 v[194:197], v218 offset:35840
	ds_read_b128 v[204:207], v218 offset:36864
	ds_read_b128 v[208:211], v218 offset:37888
	ds_read_b128 v[220:223], v218 offset:38912
	ds_read_b128 v[224:227], v218 offset:39936
	global_load_lds_dwordx4 v[104:105], off
	v_lshl_add_u64 v[104:105], s[62:63], 0, v[178:179]
	s_mov_b32 m0, s12
	s_nop 0
	global_load_lds_dwordx4 v[104:105], off
	s_setprio 1
	s_waitcnt vmcnt(8)
	s_waitcnt lgkmcnt(0)
	s_barrier
	v_mfma_f32_16x16x32_bf16 v[130:133], v[138:141], v[170:173], v[130:133]
	v_mfma_f32_16x16x32_bf16 v[126:129], v[146:149], v[170:173], v[126:129]
	v_mfma_f32_16x16x32_bf16 v[122:125], v[138:141], v[190:193], v[122:125]
	v_mfma_f32_16x16x32_bf16 v[118:121], v[146:149], v[190:193], v[118:121]
	v_mfma_f32_16x16x32_bf16 v[114:117], v[138:141], v[204:207], v[114:117]
	v_mfma_f32_16x16x32_bf16 v[110:113], v[146:149], v[204:207], v[110:113]
	v_mfma_f32_16x16x32_bf16 v[104:107], v[138:141], v[220:223], v[106:109]
	v_mfma_f32_16x16x32_bf16 v[100:103], v[146:149], v[220:223], v[100:103]
	v_mfma_f32_16x16x32_bf16 v[130:133], v[142:145], v[186:189], v[130:133]
	v_mfma_f32_16x16x32_bf16 v[126:129], v[150:153], v[186:189], v[126:129]
	v_mfma_f32_16x16x32_bf16 v[122:125], v[142:145], v[194:197], v[122:125]
	v_mfma_f32_16x16x32_bf16 v[118:121], v[150:153], v[194:197], v[118:121]
	v_mfma_f32_16x16x32_bf16 v[114:117], v[142:145], v[208:211], v[114:117]
	v_mfma_f32_16x16x32_bf16 v[110:113], v[150:153], v[208:211], v[110:113]
	v_mfma_f32_16x16x32_bf16 v[106:109], v[142:145], v[224:227], v[104:107]
	v_mfma_f32_16x16x32_bf16 v[102:105], v[150:153], v[224:227], v[100:103]
	s_setprio 0
	s_setprio 1
	v_mfma_f32_16x16x32_bf16 v[62:65], v[154:157], v[170:173], v[62:65]
	v_mfma_f32_16x16x32_bf16 v[58:61], v[162:165], v[170:173], v[58:61]
	v_mfma_f32_16x16x32_bf16 v[54:57], v[154:157], v[190:193], v[54:57]
	v_mfma_f32_16x16x32_bf16 v[50:53], v[162:165], v[190:193], v[50:53]
	v_mfma_f32_16x16x32_bf16 v[46:49], v[154:157], v[204:207], v[46:49]
	v_mfma_f32_16x16x32_bf16 v[42:45], v[162:165], v[204:207], v[42:45]
	v_mfma_f32_16x16x32_bf16 v[38:41], v[154:157], v[220:223], v[38:41]
	v_mfma_f32_16x16x32_bf16 v[34:37], v[162:165], v[220:223], v[34:37]
	v_mfma_f32_16x16x32_bf16 v[62:65], v[158:161], v[186:189], v[62:65]
	v_mfma_f32_16x16x32_bf16 v[58:61], v[166:169], v[186:189], v[58:61]
	v_mfma_f32_16x16x32_bf16 v[54:57], v[158:161], v[194:197], v[54:57]
	v_mfma_f32_16x16x32_bf16 v[50:53], v[166:169], v[194:197], v[50:53]
	v_mfma_f32_16x16x32_bf16 v[46:49], v[158:161], v[208:211], v[46:49]
	v_mfma_f32_16x16x32_bf16 v[42:45], v[166:169], v[208:211], v[42:45]
	v_mfma_f32_16x16x32_bf16 v[38:41], v[158:161], v[224:227], v[38:41]
	v_mfma_f32_16x16x32_bf16 v[34:37], v[166:169], v[224:227], v[34:37]
	s_setprio 0
	s_barrier
	s_add_i32 s62, s71, s4
	v_lshl_add_u64 v[100:101], v[198:199], 0, s[28:29]
	s_mov_b32 m0, s62
	ds_read_b128 v[170:173], v218 offset:49152
	ds_read_b128 v[186:189], v218 offset:50176
	ds_read_b128 v[190:193], v218 offset:51200
	ds_read_b128 v[194:197], v218 offset:52224
	ds_read_b128 v[204:207], v218 offset:53248
	ds_read_b128 v[208:211], v218 offset:54272
	ds_read_b128 v[220:223], v218 offset:55296
	ds_read_b128 v[224:227], v218 offset:56320
	global_load_lds_dwordx4 v[100:101], off
	s_add_i32 m0, s62, 0x2000
	s_add_u32 s60, s60, 0x40080
	v_lshl_add_u64 v[100:101], v[228:229], 0, s[28:29]
	s_addc_u32 s61, s61, 0
	s_add_i32 s62, s72, s4
	global_load_lds_dwordx4 v[100:101], off
	v_lshl_add_u64 v[100:101], s[60:61], 0, v[176:177]
	s_mov_b32 m0, s62
	s_nop 0
	global_load_lds_dwordx4 v[100:101], off
	v_lshl_add_u64 v[100:101], s[60:61], 0, v[180:181]
	s_add_i32 m0, s62, 0x2000
	s_nop 0
	global_load_lds_dwordx4 v[100:101], off
	v_lshl_add_u64 v[100:101], v[230:231], 0, s[28:29]
	s_mov_b32 m0, s15
	s_nop 0
	global_load_lds_dwordx4 v[100:101], off
	v_lshl_add_u64 v[100:101], v[232:233], 0, s[28:29]
	s_mov_b32 m0, s16
	s_nop 0
	global_load_lds_dwordx4 v[100:101], off
	s_setprio 1
	s_waitcnt vmcnt(8)
	s_waitcnt lgkmcnt(0)
	s_barrier
	v_mfma_f32_16x16x32_bf16 v[94:97], v[138:141], v[170:173], v[94:97]
	v_mfma_f32_16x16x32_bf16 v[90:93], v[146:149], v[170:173], v[90:93]
	v_mfma_f32_16x16x32_bf16 v[86:89], v[138:141], v[190:193], v[86:89]
	v_mfma_f32_16x16x32_bf16 v[82:85], v[146:149], v[190:193], v[82:85]
	v_mfma_f32_16x16x32_bf16 v[78:81], v[138:141], v[204:207], v[78:81]
	v_mfma_f32_16x16x32_bf16 v[74:77], v[146:149], v[204:207], v[74:77]
	v_mfma_f32_16x16x32_bf16 v[70:73], v[138:141], v[220:223], v[70:73]
	v_mfma_f32_16x16x32_bf16 v[66:69], v[146:149], v[220:223], v[66:69]
	v_mfma_f32_16x16x32_bf16 v[94:97], v[142:145], v[186:189], v[94:97]
	v_mfma_f32_16x16x32_bf16 v[90:93], v[150:153], v[186:189], v[90:93]
	v_mfma_f32_16x16x32_bf16 v[86:89], v[142:145], v[194:197], v[86:89]
	v_mfma_f32_16x16x32_bf16 v[82:85], v[150:153], v[194:197], v[82:85]
	v_mfma_f32_16x16x32_bf16 v[78:81], v[142:145], v[208:211], v[78:81]
	v_mfma_f32_16x16x32_bf16 v[74:77], v[150:153], v[208:211], v[74:77]
	v_mfma_f32_16x16x32_bf16 v[70:73], v[142:145], v[224:227], v[70:73]
	v_mfma_f32_16x16x32_bf16 v[66:69], v[150:153], v[224:227], v[66:69]
	s_setprio 0
	s_setprio 1
	v_mfma_f32_16x16x32_bf16 v[30:33], v[154:157], v[170:173], v[30:33]
	v_mfma_f32_16x16x32_bf16 v[26:29], v[162:165], v[170:173], v[26:29]
	v_mfma_f32_16x16x32_bf16 v[22:25], v[154:157], v[190:193], v[22:25]
	v_mfma_f32_16x16x32_bf16 v[18:21], v[162:165], v[190:193], v[18:21]
	v_mfma_f32_16x16x32_bf16 v[14:17], v[154:157], v[204:207], v[14:17]
	v_mfma_f32_16x16x32_bf16 v[10:13], v[162:165], v[204:207], v[10:13]
	v_mfma_f32_16x16x32_bf16 v[6:9], v[154:157], v[220:223], v[6:9]
	v_mfma_f32_16x16x32_bf16 v[2:5], v[162:165], v[220:223], v[2:5]
	v_mfma_f32_16x16x32_bf16 v[30:33], v[158:161], v[186:189], v[30:33]
	v_mfma_f32_16x16x32_bf16 v[26:29], v[166:169], v[186:189], v[26:29]
	v_mfma_f32_16x16x32_bf16 v[22:25], v[158:161], v[194:197], v[22:25]
	v_mfma_f32_16x16x32_bf16 v[18:21], v[166:169], v[194:197], v[18:21]
	v_mfma_f32_16x16x32_bf16 v[14:17], v[158:161], v[208:211], v[14:17]
	v_mfma_f32_16x16x32_bf16 v[10:13], v[166:169], v[208:211], v[10:13]
	v_mfma_f32_16x16x32_bf16 v[6:9], v[158:161], v[224:227], v[6:9]
	v_mfma_f32_16x16x32_bf16 v[2:5], v[166:169], v[224:227], v[2:5]
	s_setprio 0
	s_barrier
	s_add_u32 s58, s58, 0x100
	s_addc_u32 s59, s59, 0
	s_cmp_gt_u32 s70, 13
	s_cbranch_scc1 .LBB0_1075

.LBB0_1110:
	s_add_i32 s75, s75, 2
	s_add_u32 s60, s38, s58
	s_addc_u32 s61, s39, s59
	s_add_u32 s60, s60, 0x100
	s_addc_u32 s61, s61, 0
	s_add_u32 s76, s72, s58
	s_addc_u32 s77, s73, s59
	s_add_i32 s78, 0, 0x10000
	s_cmp_eq_u32 s74, s58
	s_cselect_b32 s63, s49, s61
	s_cselect_b32 s62, s70, s60
	v_add_u32_e32 v98, s78, v177
	s_cselect_b32 s61, s45, s77
	s_cselect_b32 s60, s71, s76
	s_add_i32 s79, 0, 0x14000
	ds_read_b128 v[138:141], v98
	ds_read_b128 v[142:145], v98 offset:1024
	ds_read_b128 v[146:149], v98 offset:2048
	ds_read_b128 v[150:153], v98 offset:3072
	v_add_u32_e32 v98, s79, v177
	ds_read_b128 v[154:157], v98
	ds_read_b128 v[170:173], v98 offset:1024
	ds_read_b128 v[182:185], v98 offset:2048
	ds_read_b128 v[186:189], v98 offset:3072
	v_lshl_add_u64 v[100:101], v[134:135], 0, s[58:59]
	s_add_i32 m0, s10, 0xc000
	ds_read_b128 v[190:193], v181
	ds_read_b128 v[194:197], v181 offset:1024
	ds_read_b128 v[204:207], v181 offset:2048
	ds_read_b128 v[208:211], v181 offset:3072
	ds_read_b128 v[214:217], v181 offset:4096
	ds_read_b128 v[218:221], v181 offset:5120
	ds_read_b128 v[222:225], v181 offset:6144
	ds_read_b128 v[226:229], v181 offset:7168
	global_load_lds_dwordx4 v[100:101], off
	v_lshl_add_u64 v[100:101], v[136:137], 0, s[58:59]
	s_add_i32 m0, s10, 0xe000
	s_nop 0
	global_load_lds_dwordx4 v[100:101], off
	s_setprio 1
	s_waitcnt vmcnt(8)
	s_waitcnt lgkmcnt(0)
	s_barrier
	v_mfma_f32_16x16x32_bf16 v[130:133], v[138:141], v[190:193], v[130:133]
	v_mfma_f32_16x16x32_bf16 v[126:129], v[146:149], v[190:193], v[126:129]
	v_mfma_f32_16x16x32_bf16 v[114:117], v[138:141], v[204:207], v[114:117]
	v_mfma_f32_16x16x32_bf16 v[110:113], v[146:149], v[204:207], v[110:113]
	v_mfma_f32_16x16x32_bf16 v[94:97], v[138:141], v[214:217], v[94:97]
	v_mfma_f32_16x16x32_bf16 v[90:93], v[146:149], v[214:217], v[90:93]
	v_mfma_f32_16x16x32_bf16 v[78:81], v[138:141], v[222:225], v[78:81]
	v_mfma_f32_16x16x32_bf16 v[74:77], v[146:149], v[222:225], v[74:77]
	v_mfma_f32_16x16x32_bf16 v[130:133], v[142:145], v[194:197], v[130:133]
	v_mfma_f32_16x16x32_bf16 v[126:129], v[150:153], v[194:197], v[126:129]
	v_mfma_f32_16x16x32_bf16 v[114:117], v[142:145], v[208:211], v[114:117]
	v_mfma_f32_16x16x32_bf16 v[110:113], v[150:153], v[208:211], v[110:113]
	v_mfma_f32_16x16x32_bf16 v[94:97], v[142:145], v[218:221], v[94:97]
	v_mfma_f32_16x16x32_bf16 v[90:93], v[150:153], v[218:221], v[90:93]
	v_mfma_f32_16x16x32_bf16 v[78:81], v[142:145], v[226:229], v[78:81]
	v_mfma_f32_16x16x32_bf16 v[74:77], v[150:153], v[226:229], v[74:77]
	s_setprio 0
	s_setprio 1
	v_mfma_f32_16x16x32_bf16 v[122:125], v[154:157], v[190:193], v[122:125]
	v_mfma_f32_16x16x32_bf16 v[118:121], v[182:185], v[190:193], v[118:121]
	v_mfma_f32_16x16x32_bf16 v[106:109], v[154:157], v[204:207], v[106:109]
	v_mfma_f32_16x16x32_bf16 v[100:103], v[182:185], v[204:207], v[102:105]
	v_mfma_f32_16x16x32_bf16 v[86:89], v[154:157], v[214:217], v[86:89]
	v_mfma_f32_16x16x32_bf16 v[82:85], v[182:185], v[214:217], v[82:85]
	v_mfma_f32_16x16x32_bf16 v[70:73], v[154:157], v[222:225], v[70:73]
	v_mfma_f32_16x16x32_bf16 v[66:69], v[182:185], v[222:225], v[66:69]
	v_mfma_f32_16x16x32_bf16 v[122:125], v[170:173], v[194:197], v[122:125]
	v_mfma_f32_16x16x32_bf16 v[118:121], v[186:189], v[194:197], v[118:121]
	v_mfma_f32_16x16x32_bf16 v[106:109], v[170:173], v[208:211], v[106:109]
	v_mfma_f32_16x16x32_bf16 v[100:103], v[186:189], v[208:211], v[100:103]
	v_mfma_f32_16x16x32_bf16 v[86:89], v[170:173], v[218:221], v[86:89]
	v_mfma_f32_16x16x32_bf16 v[82:85], v[186:189], v[218:221], v[82:85]
	v_mfma_f32_16x16x32_bf16 v[70:73], v[170:173], v[226:229], v[70:73]
	v_mfma_f32_16x16x32_bf16 v[66:69], v[186:189], v[226:229], v[66:69]
	s_setprio 0
	s_barrier
	s_add_i32 s76, s78, s9
	v_lshl_add_u64 v[174:175], s[60:61], 0, v[162:163]
	s_mov_b32 m0, s76
	ds_read_b128 v[190:193], v181 offset:16384
	ds_read_b128 v[194:197], v181 offset:17408
	ds_read_b128 v[204:207], v181 offset:18432
	ds_read_b128 v[208:211], v181 offset:19456
	ds_read_b128 v[214:217], v181 offset:20480
	ds_read_b128 v[218:221], v181 offset:21504
	ds_read_b128 v[222:225], v181 offset:22528
	ds_read_b128 v[226:229], v181 offset:23552
	global_load_lds_dwordx4 v[174:175], off
	s_add_i32 m0, s76, 0x2000
	s_add_u32 s76, s60, 0x40000
	v_lshl_add_u64 v[198:199], s[60:61], 0, v[158:159]
	s_addc_u32 s77, s61, 0
	s_add_i32 s78, s79, s9
	global_load_lds_dwordx4 v[198:199], off
	v_lshl_add_u64 v[104:105], s[76:77], 0, v[162:163]
	s_mov_b32 m0, s78
	v_lshl_add_u64 v[230:231], s[62:63], 0, v[164:165]
	global_load_lds_dwordx4 v[104:105], off
	v_lshl_add_u64 v[104:105], s[76:77], 0, v[158:159]
	s_add_i32 m0, s78, 0x2000
	v_lshl_add_u64 v[232:233], s[62:63], 0, v[160:161]
	global_load_lds_dwordx4 v[104:105], off
	s_mov_b32 m0, s10
	s_nop 0
	global_load_lds_dwordx4 v[230:231], off
	s_mov_b32 m0, s11
	s_nop 0
	global_load_lds_dwordx4 v[232:233], off
	s_setprio 1
	s_waitcnt vmcnt(8)
	s_waitcnt lgkmcnt(0)
	s_barrier
	v_mfma_f32_16x16x32_bf16 v[62:65], v[138:141], v[190:193], v[62:65]
	v_mfma_f32_16x16x32_bf16 v[58:61], v[146:149], v[190:193], v[58:61]
	v_mfma_f32_16x16x32_bf16 v[46:49], v[138:141], v[204:207], v[46:49]
	v_mfma_f32_16x16x32_bf16 v[42:45], v[146:149], v[204:207], v[42:45]
	v_mfma_f32_16x16x32_bf16 v[30:33], v[138:141], v[214:217], v[30:33]
	v_mfma_f32_16x16x32_bf16 v[26:29], v[146:149], v[214:217], v[26:29]
	v_mfma_f32_16x16x32_bf16 v[14:17], v[138:141], v[222:225], v[14:17]
	v_mfma_f32_16x16x32_bf16 v[10:13], v[146:149], v[222:225], v[10:13]
	v_mfma_f32_16x16x32_bf16 v[62:65], v[142:145], v[194:197], v[62:65]
	v_mfma_f32_16x16x32_bf16 v[58:61], v[150:153], v[194:197], v[58:61]
	v_mfma_f32_16x16x32_bf16 v[46:49], v[142:145], v[208:211], v[46:49]
	v_mfma_f32_16x16x32_bf16 v[42:45], v[150:153], v[208:211], v[42:45]
	v_mfma_f32_16x16x32_bf16 v[30:33], v[142:145], v[218:221], v[30:33]
	v_mfma_f32_16x16x32_bf16 v[26:29], v[150:153], v[218:221], v[26:29]
	v_mfma_f32_16x16x32_bf16 v[14:17], v[142:145], v[226:229], v[14:17]
	v_mfma_f32_16x16x32_bf16 v[10:13], v[150:153], v[226:229], v[10:13]
	s_setprio 0
	s_setprio 1
	v_mfma_f32_16x16x32_bf16 v[54:57], v[154:157], v[190:193], v[54:57]
	v_mfma_f32_16x16x32_bf16 v[50:53], v[182:185], v[190:193], v[50:53]
	v_mfma_f32_16x16x32_bf16 v[38:41], v[154:157], v[204:207], v[38:41]
	v_mfma_f32_16x16x32_bf16 v[34:37], v[182:185], v[204:207], v[34:37]
	v_mfma_f32_16x16x32_bf16 v[22:25], v[154:157], v[214:217], v[22:25]
	v_mfma_f32_16x16x32_bf16 v[18:21], v[182:185], v[214:217], v[18:21]
	v_mfma_f32_16x16x32_bf16 v[6:9], v[154:157], v[222:225], v[6:9]
	v_mfma_f32_16x16x32_bf16 v[2:5], v[182:185], v[222:225], v[2:5]
	v_mfma_f32_16x16x32_bf16 v[54:57], v[170:173], v[194:197], v[54:57]
	v_mfma_f32_16x16x32_bf16 v[50:53], v[186:189], v[194:197], v[50:53]
	v_mfma_f32_16x16x32_bf16 v[38:41], v[170:173], v[208:211], v[38:41]
	v_mfma_f32_16x16x32_bf16 v[34:37], v[186:189], v[208:211], v[34:37]
	v_mfma_f32_16x16x32_bf16 v[22:25], v[170:173], v[218:221], v[22:25]
	v_mfma_f32_16x16x32_bf16 v[18:21], v[186:189], v[218:221], v[18:21]
	v_mfma_f32_16x16x32_bf16 v[6:9], v[170:173], v[226:229], v[6:9]
	v_mfma_f32_16x16x32_bf16 v[2:5], v[186:189], v[226:229], v[2:5]
	s_setprio 0
	s_barrier
	s_add_i32 s76, 0, 0x18000
	v_add_u32_e32 v98, s76, v177
	s_add_i32 s77, 0, 0x1c000
	ds_read_b128 v[138:141], v98
	ds_read_b128 v[142:145], v98 offset:1024
	ds_read_b128 v[146:149], v98 offset:2048
	ds_read_b128 v[150:153], v98 offset:3072
	v_add_u32_e32 v98, s77, v177
	ds_read_b128 v[154:157], v98
	ds_read_b128 v[170:173], v98 offset:1024
	ds_read_b128 v[182:185], v98 offset:2048
	ds_read_b128 v[186:189], v98 offset:3072
	s_add_u32 s62, s62, 0x40000
	s_addc_u32 s63, s63, 0
	s_mov_b32 m0, s12
	v_lshl_add_u64 v[104:105], s[62:63], 0, v[164:165]
	ds_read_b128 v[190:193], v181 offset:32768
	ds_read_b128 v[194:197], v181 offset:33792
	ds_read_b128 v[204:207], v181 offset:34816
	ds_read_b128 v[208:211], v181 offset:35840
	ds_read_b128 v[214:217], v181 offset:36864
	ds_read_b128 v[218:221], v181 offset:37888
	ds_read_b128 v[222:225], v181 offset:38912
	ds_read_b128 v[226:229], v181 offset:39936
	global_load_lds_dwordx4 v[104:105], off
	v_lshl_add_u64 v[104:105], s[62:63], 0, v[160:161]
	s_mov_b32 m0, s13
	s_nop 0
	global_load_lds_dwordx4 v[104:105], off
	s_setprio 1
	s_waitcnt vmcnt(8)
	s_waitcnt lgkmcnt(0)
	s_barrier
	v_mfma_f32_16x16x32_bf16 v[130:133], v[138:141], v[190:193], v[130:133]
	v_mfma_f32_16x16x32_bf16 v[126:129], v[146:149], v[190:193], v[126:129]
	v_mfma_f32_16x16x32_bf16 v[114:117], v[138:141], v[204:207], v[114:117]
	v_mfma_f32_16x16x32_bf16 v[110:113], v[146:149], v[204:207], v[110:113]
	v_mfma_f32_16x16x32_bf16 v[94:97], v[138:141], v[214:217], v[94:97]
	v_mfma_f32_16x16x32_bf16 v[90:93], v[146:149], v[214:217], v[90:93]
	v_mfma_f32_16x16x32_bf16 v[78:81], v[138:141], v[222:225], v[78:81]
	v_mfma_f32_16x16x32_bf16 v[74:77], v[146:149], v[222:225], v[74:77]
	v_mfma_f32_16x16x32_bf16 v[130:133], v[142:145], v[194:197], v[130:133]
	v_mfma_f32_16x16x32_bf16 v[126:129], v[150:153], v[194:197], v[126:129]
	v_mfma_f32_16x16x32_bf16 v[114:117], v[142:145], v[208:211], v[114:117]
	v_mfma_f32_16x16x32_bf16 v[110:113], v[150:153], v[208:211], v[110:113]
	v_mfma_f32_16x16x32_bf16 v[94:97], v[142:145], v[218:221], v[94:97]
	v_mfma_f32_16x16x32_bf16 v[90:93], v[150:153], v[218:221], v[90:93]
	v_mfma_f32_16x16x32_bf16 v[78:81], v[142:145], v[226:229], v[78:81]
	v_mfma_f32_16x16x32_bf16 v[74:77], v[150:153], v[226:229], v[74:77]
	s_setprio 0
	s_setprio 1
	v_mfma_f32_16x16x32_bf16 v[122:125], v[154:157], v[190:193], v[122:125]
	v_mfma_f32_16x16x32_bf16 v[118:121], v[182:185], v[190:193], v[118:121]
	v_mfma_f32_16x16x32_bf16 v[104:107], v[154:157], v[204:207], v[106:109]
	v_mfma_f32_16x16x32_bf16 v[100:103], v[182:185], v[204:207], v[100:103]
	v_mfma_f32_16x16x32_bf16 v[86:89], v[154:157], v[214:217], v[86:89]
	v_mfma_f32_16x16x32_bf16 v[82:85], v[182:185], v[214:217], v[82:85]
	v_mfma_f32_16x16x32_bf16 v[70:73], v[154:157], v[222:225], v[70:73]
	v_mfma_f32_16x16x32_bf16 v[66:69], v[182:185], v[222:225], v[66:69]
	v_mfma_f32_16x16x32_bf16 v[122:125], v[170:173], v[194:197], v[122:125]
	v_mfma_f32_16x16x32_bf16 v[118:121], v[186:189], v[194:197], v[118:121]
	v_mfma_f32_16x16x32_bf16 v[106:109], v[170:173], v[208:211], v[104:107]
	v_mfma_f32_16x16x32_bf16 v[102:105], v[186:189], v[208:211], v[100:103]
	v_mfma_f32_16x16x32_bf16 v[86:89], v[170:173], v[218:221], v[86:89]
	v_mfma_f32_16x16x32_bf16 v[82:85], v[186:189], v[218:221], v[82:85]
	v_mfma_f32_16x16x32_bf16 v[70:73], v[170:173], v[226:229], v[70:73]
	v_mfma_f32_16x16x32_bf16 v[66:69], v[186:189], v[226:229], v[66:69]
	s_setprio 0
	s_barrier
	s_add_i32 s62, s76, s9
	v_lshl_add_u64 v[100:101], v[174:175], 0, s[28:29]
	s_mov_b32 m0, s62
	ds_read_b128 v[190:193], v181 offset:49152
	ds_read_b128 v[194:197], v181 offset:50176
	ds_read_b128 v[204:207], v181 offset:51200
	ds_read_b128 v[208:211], v181 offset:52224
	ds_read_b128 v[214:217], v181 offset:53248
	ds_read_b128 v[218:221], v181 offset:54272
	ds_read_b128 v[222:225], v181 offset:55296
	ds_read_b128 v[226:229], v181 offset:56320
	global_load_lds_dwordx4 v[100:101], off
	s_add_i32 m0, s62, 0x2000
	s_add_u32 s60, s60, 0x40080
	v_lshl_add_u64 v[100:101], v[198:199], 0, s[28:29]
	s_addc_u32 s61, s61, 0
	s_add_i32 s62, s77, s9
	global_load_lds_dwordx4 v[100:101], off
	v_lshl_add_u64 v[100:101], s[60:61], 0, v[162:163]
	s_mov_b32 m0, s62
	s_nop 0
	global_load_lds_dwordx4 v[100:101], off
	v_lshl_add_u64 v[100:101], s[60:61], 0, v[158:159]
	s_add_i32 m0, s62, 0x2000
	s_nop 0
	global_load_lds_dwordx4 v[100:101], off
	v_lshl_add_u64 v[100:101], v[230:231], 0, s[28:29]
	s_mov_b32 m0, s16
	s_nop 0
	global_load_lds_dwordx4 v[100:101], off
	v_lshl_add_u64 v[100:101], v[232:233], 0, s[28:29]
	s_mov_b32 m0, s17
	s_nop 0
	global_load_lds_dwordx4 v[100:101], off
	s_setprio 1
	s_waitcnt vmcnt(8)
	s_waitcnt lgkmcnt(0)
	s_barrier
	v_mfma_f32_16x16x32_bf16 v[62:65], v[138:141], v[190:193], v[62:65]
	v_mfma_f32_16x16x32_bf16 v[58:61], v[146:149], v[190:193], v[58:61]
	v_mfma_f32_16x16x32_bf16 v[46:49], v[138:141], v[204:207], v[46:49]
	v_mfma_f32_16x16x32_bf16 v[42:45], v[146:149], v[204:207], v[42:45]
	v_mfma_f32_16x16x32_bf16 v[30:33], v[138:141], v[214:217], v[30:33]
	v_mfma_f32_16x16x32_bf16 v[26:29], v[146:149], v[214:217], v[26:29]
	v_mfma_f32_16x16x32_bf16 v[14:17], v[138:141], v[222:225], v[14:17]
	v_mfma_f32_16x16x32_bf16 v[10:13], v[146:149], v[222:225], v[10:13]
	v_mfma_f32_16x16x32_bf16 v[62:65], v[142:145], v[194:197], v[62:65]
	v_mfma_f32_16x16x32_bf16 v[58:61], v[150:153], v[194:197], v[58:61]
	v_mfma_f32_16x16x32_bf16 v[46:49], v[142:145], v[208:211], v[46:49]
	v_mfma_f32_16x16x32_bf16 v[42:45], v[150:153], v[208:211], v[42:45]
	v_mfma_f32_16x16x32_bf16 v[30:33], v[142:145], v[218:221], v[30:33]
	v_mfma_f32_16x16x32_bf16 v[26:29], v[150:153], v[218:221], v[26:29]
	v_mfma_f32_16x16x32_bf16 v[14:17], v[142:145], v[226:229], v[14:17]
	v_mfma_f32_16x16x32_bf16 v[10:13], v[150:153], v[226:229], v[10:13]
	s_setprio 0
	s_setprio 1
	v_mfma_f32_16x16x32_bf16 v[54:57], v[154:157], v[190:193], v[54:57]
	v_mfma_f32_16x16x32_bf16 v[50:53], v[182:185], v[190:193], v[50:53]
	v_mfma_f32_16x16x32_bf16 v[38:41], v[154:157], v[204:207], v[38:41]
	v_mfma_f32_16x16x32_bf16 v[34:37], v[182:185], v[204:207], v[34:37]
	v_mfma_f32_16x16x32_bf16 v[22:25], v[154:157], v[214:217], v[22:25]
	v_mfma_f32_16x16x32_bf16 v[18:21], v[182:185], v[214:217], v[18:21]
	v_mfma_f32_16x16x32_bf16 v[6:9], v[154:157], v[222:225], v[6:9]
	v_mfma_f32_16x16x32_bf16 v[2:5], v[182:185], v[222:225], v[2:5]
	v_mfma_f32_16x16x32_bf16 v[54:57], v[170:173], v[194:197], v[54:57]
	v_mfma_f32_16x16x32_bf16 v[50:53], v[186:189], v[194:197], v[50:53]
	v_mfma_f32_16x16x32_bf16 v[38:41], v[170:173], v[208:211], v[38:41]
	v_mfma_f32_16x16x32_bf16 v[34:37], v[186:189], v[208:211], v[34:37]
	v_mfma_f32_16x16x32_bf16 v[22:25], v[170:173], v[218:221], v[22:25]
	v_mfma_f32_16x16x32_bf16 v[18:21], v[186:189], v[218:221], v[18:21]
	v_mfma_f32_16x16x32_bf16 v[6:9], v[170:173], v[226:229], v[6:9]
	v_mfma_f32_16x16x32_bf16 v[2:5], v[186:189], v[226:229], v[2:5]
	s_setprio 0
	s_barrier
	s_add_u32 s58, s58, 0x100
	s_addc_u32 s59, s59, 0
	s_cmp_ge_u32 s75, s57
	s_cbranch_scc1 .LBB0_1113

.LBB0_1328:
	s_add_u32 s44, s42, 0xfffc0080
	s_addc_u32 s45, s43, -1
	s_add_i32 s53, 0, 0x10000
	s_cmp_eq_u32 s52, 12
	s_cselect_b32 s47, s1, s45
	s_cselect_b32 s46, s41, s44
	s_cselect_b32 s45, s48, s51
	s_cselect_b32 s44, s49, s50
	s_add_i32 s56, 0, 0x14000
	v_add_u32_e32 v94, s53, v186
	v_add_u32_e32 v174, s56, v186
	ds_read_b128 v[82:85], v94
	ds_read_b128 v[86:89], v94 offset:1024
	ds_read_b128 v[90:93], v94 offset:2048
	ds_read_b128 v[94:97], v94 offset:3072
	ds_read_b128 v[162:165], v174
	ds_read_b128 v[166:169], v174 offset:1024
	ds_read_b128 v[170:173], v174 offset:2048
	ds_read_b128 v[174:177], v174 offset:3072
	s_add_u32 s100, s42, 0xfffc0000
	s_addc_u32 s101, s43, -1
	v_lshl_add_u64 v[198:199], s[100:101], 0, v[148:149]
	s_mov_b32 m0, s33
	s_nop 0
	global_load_lds_dwordx4 v[198:199], off
	v_lshl_add_u64 v[198:199], s[100:101], 0, v[150:151]
	s_mov_b32 m0, s14
	s_nop 0
	global_load_lds_dwordx4 v[198:199], off
	v_lshl_add_u64 v[198:199], s[42:43], 0, v[158:159]
	s_add_i32 m0, s2, 0xc000
	ds_read_b128 v[178:181], v187
	ds_read_b128 v[182:185], v187 offset:1024
	ds_read_b128 v[190:193], v187 offset:2048
	ds_read_b128 v[194:197], v187 offset:3072
	ds_read_b128 v[204:207], v187 offset:4096
	ds_read_b128 v[208:211], v187 offset:5120
	ds_read_b128 v[214:217], v187 offset:6144
	ds_read_b128 v[218:221], v187 offset:7168
	global_load_lds_dwordx4 v[198:199], off
	v_lshl_add_u64 v[198:199], s[42:43], 0, v[160:161]
	s_add_i32 m0, s2, 0xe000
	s_nop 0
	global_load_lds_dwordx4 v[198:199], off
	s_setprio 1
	s_waitcnt vmcnt(8)
	s_waitcnt lgkmcnt(0)
	s_barrier
	v_mfma_f32_16x16x32_bf16 v[144:147], v[82:85], v[178:181], v[144:147]
	v_mfma_f32_16x16x32_bf16 v[140:143], v[90:93], v[178:181], v[140:143]
	v_mfma_f32_16x16x32_bf16 v[128:131], v[82:85], v[190:193], v[128:131]
	v_mfma_f32_16x16x32_bf16 v[124:127], v[90:93], v[190:193], v[124:127]
	v_mfma_f32_16x16x32_bf16 v[112:115], v[82:85], v[204:207], v[112:115]
	v_mfma_f32_16x16x32_bf16 v[108:111], v[90:93], v[204:207], v[108:111]
	v_mfma_f32_16x16x32_bf16 v[78:81], v[82:85], v[214:217], v[78:81]
	v_mfma_f32_16x16x32_bf16 v[74:77], v[90:93], v[214:217], v[74:77]
	v_mfma_f32_16x16x32_bf16 v[144:147], v[86:89], v[182:185], v[144:147]
	v_mfma_f32_16x16x32_bf16 v[140:143], v[94:97], v[182:185], v[140:143]
	v_mfma_f32_16x16x32_bf16 v[128:131], v[86:89], v[194:197], v[128:131]
	v_mfma_f32_16x16x32_bf16 v[124:127], v[94:97], v[194:197], v[124:127]
	v_mfma_f32_16x16x32_bf16 v[112:115], v[86:89], v[208:211], v[112:115]
	v_mfma_f32_16x16x32_bf16 v[108:111], v[94:97], v[208:211], v[108:111]
	v_mfma_f32_16x16x32_bf16 v[78:81], v[86:89], v[218:221], v[78:81]
	v_mfma_f32_16x16x32_bf16 v[74:77], v[94:97], v[218:221], v[74:77]
	s_setprio 0
	s_setprio 1
	v_mfma_f32_16x16x32_bf16 v[136:139], v[162:165], v[178:181], v[136:139]
	v_mfma_f32_16x16x32_bf16 v[132:135], v[170:173], v[178:181], v[132:135]
	v_mfma_f32_16x16x32_bf16 v[120:123], v[162:165], v[190:193], v[120:123]
	v_mfma_f32_16x16x32_bf16 v[116:119], v[170:173], v[190:193], v[116:119]
	v_mfma_f32_16x16x32_bf16 v[104:107], v[162:165], v[204:207], v[104:107]
	v_mfma_f32_16x16x32_bf16 v[100:103], v[170:173], v[204:207], v[100:103]
	v_mfma_f32_16x16x32_bf16 v[70:73], v[162:165], v[214:217], v[70:73]
	v_mfma_f32_16x16x32_bf16 v[66:69], v[170:173], v[214:217], v[66:69]
	v_mfma_f32_16x16x32_bf16 v[136:139], v[166:169], v[182:185], v[136:139]
	v_mfma_f32_16x16x32_bf16 v[132:135], v[174:177], v[182:185], v[132:135]
	v_mfma_f32_16x16x32_bf16 v[120:123], v[166:169], v[194:197], v[120:123]
	v_mfma_f32_16x16x32_bf16 v[116:119], v[174:177], v[194:197], v[116:119]
	v_mfma_f32_16x16x32_bf16 v[104:107], v[166:169], v[208:211], v[104:107]
	v_mfma_f32_16x16x32_bf16 v[100:103], v[174:177], v[208:211], v[100:103]
	v_mfma_f32_16x16x32_bf16 v[70:73], v[166:169], v[218:221], v[70:73]
	v_mfma_f32_16x16x32_bf16 v[66:69], v[174:177], v[218:221], v[66:69]
	s_setprio 0
	s_barrier
	s_add_i32 s53, s53, s9
	v_lshl_add_u64 v[198:199], s[44:45], 0, v[98:99]
	s_mov_b32 m0, s53
	ds_read_b128 v[178:181], v187 offset:16384
	ds_read_b128 v[182:185], v187 offset:17408
	ds_read_b128 v[190:193], v187 offset:18432
	ds_read_b128 v[194:197], v187 offset:19456
	ds_read_b128 v[204:207], v187 offset:20480
	ds_read_b128 v[208:211], v187 offset:21504
	ds_read_b128 v[214:217], v187 offset:22528
	ds_read_b128 v[218:221], v187 offset:23552
	global_load_lds_dwordx4 v[198:199], off
	s_add_i32 m0, s53, 0x2000
	s_add_u32 s54, s44, 0x40000
	v_lshl_add_u64 v[222:223], s[44:45], 0, v[152:153]
	s_addc_u32 s55, s45, 0
	s_add_i32 s53, s56, s9
	global_load_lds_dwordx4 v[222:223], off
	v_lshl_add_u64 v[224:225], s[54:55], 0, v[98:99]
	s_mov_b32 m0, s53
	s_nop 0
	global_load_lds_dwordx4 v[224:225], off
	v_lshl_add_u64 v[224:225], s[54:55], 0, v[152:153]
	s_add_i32 m0, s53, 0x2000
	s_nop 0
	global_load_lds_dwordx4 v[224:225], off
	s_setprio 1
	s_waitcnt vmcnt(6)
	s_waitcnt lgkmcnt(0)
	s_barrier
	v_mfma_f32_16x16x32_bf16 v[62:65], v[82:85], v[178:181], v[62:65]
	v_mfma_f32_16x16x32_bf16 v[58:61], v[90:93], v[178:181], v[58:61]
	v_mfma_f32_16x16x32_bf16 v[46:49], v[82:85], v[190:193], v[46:49]
	v_mfma_f32_16x16x32_bf16 v[42:45], v[90:93], v[190:193], v[42:45]
	v_mfma_f32_16x16x32_bf16 v[30:33], v[82:85], v[204:207], v[30:33]
	v_mfma_f32_16x16x32_bf16 v[26:29], v[90:93], v[204:207], v[26:29]
	v_mfma_f32_16x16x32_bf16 v[14:17], v[82:85], v[214:217], v[14:17]
	v_mfma_f32_16x16x32_bf16 v[10:13], v[90:93], v[214:217], v[10:13]
	v_mfma_f32_16x16x32_bf16 v[62:65], v[86:89], v[182:185], v[62:65]
	v_mfma_f32_16x16x32_bf16 v[58:61], v[94:97], v[182:185], v[58:61]
	v_mfma_f32_16x16x32_bf16 v[46:49], v[86:89], v[194:197], v[46:49]
	v_mfma_f32_16x16x32_bf16 v[42:45], v[94:97], v[194:197], v[42:45]
	v_mfma_f32_16x16x32_bf16 v[30:33], v[86:89], v[208:211], v[30:33]
	v_mfma_f32_16x16x32_bf16 v[26:29], v[94:97], v[208:211], v[26:29]
	v_mfma_f32_16x16x32_bf16 v[14:17], v[86:89], v[218:221], v[14:17]
	v_mfma_f32_16x16x32_bf16 v[10:13], v[94:97], v[218:221], v[10:13]
	s_setprio 0
	s_setprio 1
	v_mfma_f32_16x16x32_bf16 v[54:57], v[162:165], v[178:181], v[54:57]
	v_mfma_f32_16x16x32_bf16 v[50:53], v[170:173], v[178:181], v[50:53]
	v_mfma_f32_16x16x32_bf16 v[38:41], v[162:165], v[190:193], v[38:41]
	v_mfma_f32_16x16x32_bf16 v[34:37], v[170:173], v[190:193], v[34:37]
	v_mfma_f32_16x16x32_bf16 v[22:25], v[162:165], v[204:207], v[22:25]
	v_mfma_f32_16x16x32_bf16 v[18:21], v[170:173], v[204:207], v[18:21]
	v_mfma_f32_16x16x32_bf16 v[6:9], v[162:165], v[214:217], v[6:9]
	v_mfma_f32_16x16x32_bf16 v[2:5], v[170:173], v[214:217], v[2:5]
	v_mfma_f32_16x16x32_bf16 v[54:57], v[166:169], v[182:185], v[54:57]
	v_mfma_f32_16x16x32_bf16 v[50:53], v[174:177], v[182:185], v[50:53]
	v_mfma_f32_16x16x32_bf16 v[38:41], v[166:169], v[194:197], v[38:41]
	v_mfma_f32_16x16x32_bf16 v[34:37], v[174:177], v[194:197], v[34:37]
	v_mfma_f32_16x16x32_bf16 v[22:25], v[166:169], v[208:211], v[22:25]
	v_mfma_f32_16x16x32_bf16 v[18:21], v[174:177], v[208:211], v[18:21]
	v_mfma_f32_16x16x32_bf16 v[6:9], v[166:169], v[218:221], v[6:9]
	v_mfma_f32_16x16x32_bf16 v[2:5], v[174:177], v[218:221], v[2:5]
	s_setprio 0
	s_barrier
	s_add_i32 s53, 0, 0x18000
	s_add_i32 s54, 0, 0x1c000
	v_add_u32_e32 v94, s53, v186
	v_add_u32_e32 v174, s54, v186
	ds_read_b128 v[82:85], v94
	ds_read_b128 v[86:89], v94 offset:1024
	ds_read_b128 v[90:93], v94 offset:2048
	ds_read_b128 v[94:97], v94 offset:3072
	ds_read_b128 v[162:165], v174
	ds_read_b128 v[166:169], v174 offset:1024
	ds_read_b128 v[170:173], v174 offset:2048
	ds_read_b128 v[174:177], v174 offset:3072
	v_lshl_add_u64 v[224:225], s[46:47], 0, v[148:149]
	s_mov_b32 m0, s2
	v_lshl_add_u64 v[226:227], s[46:47], 0, v[150:151]
	global_load_lds_dwordx4 v[224:225], off
	s_mov_b32 m0, s4
	s_nop 0
	global_load_lds_dwordx4 v[226:227], off
	s_add_u32 s46, s46, 0x40000
	s_addc_u32 s47, s47, 0
	s_mov_b32 m0, s12
	v_lshl_add_u64 v[228:229], s[46:47], 0, v[148:149]
	ds_read_b128 v[178:181], v187 offset:32768
	ds_read_b128 v[182:185], v187 offset:33792
	ds_read_b128 v[190:193], v187 offset:34816
	ds_read_b128 v[194:197], v187 offset:35840
	ds_read_b128 v[204:207], v187 offset:36864
	ds_read_b128 v[208:211], v187 offset:37888
	ds_read_b128 v[214:217], v187 offset:38912
	ds_read_b128 v[218:221], v187 offset:39936
	global_load_lds_dwordx4 v[228:229], off
	v_lshl_add_u64 v[228:229], s[46:47], 0, v[150:151]
	s_mov_b32 m0, s13
	s_nop 0
	global_load_lds_dwordx4 v[228:229], off
	s_setprio 1
	s_waitcnt vmcnt(8)
	s_waitcnt lgkmcnt(0)
	s_barrier
	v_mfma_f32_16x16x32_bf16 v[144:147], v[82:85], v[178:181], v[144:147]
	v_mfma_f32_16x16x32_bf16 v[140:143], v[90:93], v[178:181], v[140:143]
	v_mfma_f32_16x16x32_bf16 v[128:131], v[82:85], v[190:193], v[128:131]
	v_mfma_f32_16x16x32_bf16 v[124:127], v[90:93], v[190:193], v[124:127]
	v_mfma_f32_16x16x32_bf16 v[112:115], v[82:85], v[204:207], v[112:115]
	v_mfma_f32_16x16x32_bf16 v[108:111], v[90:93], v[204:207], v[108:111]
	v_mfma_f32_16x16x32_bf16 v[78:81], v[82:85], v[214:217], v[78:81]
	v_mfma_f32_16x16x32_bf16 v[74:77], v[90:93], v[214:217], v[74:77]
	v_mfma_f32_16x16x32_bf16 v[144:147], v[86:89], v[182:185], v[144:147]
	v_mfma_f32_16x16x32_bf16 v[140:143], v[94:97], v[182:185], v[140:143]
	v_mfma_f32_16x16x32_bf16 v[128:131], v[86:89], v[194:197], v[128:131]
	v_mfma_f32_16x16x32_bf16 v[124:127], v[94:97], v[194:197], v[124:127]
	v_mfma_f32_16x16x32_bf16 v[112:115], v[86:89], v[208:211], v[112:115]
	v_mfma_f32_16x16x32_bf16 v[108:111], v[94:97], v[208:211], v[108:111]
	v_mfma_f32_16x16x32_bf16 v[78:81], v[86:89], v[218:221], v[78:81]
	v_mfma_f32_16x16x32_bf16 v[74:77], v[94:97], v[218:221], v[74:77]
	s_setprio 0
	s_setprio 1
	v_mfma_f32_16x16x32_bf16 v[136:139], v[162:165], v[178:181], v[136:139]
	v_mfma_f32_16x16x32_bf16 v[132:135], v[170:173], v[178:181], v[132:135]
	v_mfma_f32_16x16x32_bf16 v[120:123], v[162:165], v[190:193], v[120:123]
	v_mfma_f32_16x16x32_bf16 v[116:119], v[170:173], v[190:193], v[116:119]
	v_mfma_f32_16x16x32_bf16 v[104:107], v[162:165], v[204:207], v[104:107]
	v_mfma_f32_16x16x32_bf16 v[100:103], v[170:173], v[204:207], v[100:103]
	v_mfma_f32_16x16x32_bf16 v[70:73], v[162:165], v[214:217], v[70:73]
	v_mfma_f32_16x16x32_bf16 v[66:69], v[170:173], v[214:217], v[66:69]
	v_mfma_f32_16x16x32_bf16 v[136:139], v[166:169], v[182:185], v[136:139]
	v_mfma_f32_16x16x32_bf16 v[132:135], v[174:177], v[182:185], v[132:135]
	v_mfma_f32_16x16x32_bf16 v[120:123], v[166:169], v[194:197], v[120:123]
	v_mfma_f32_16x16x32_bf16 v[116:119], v[174:177], v[194:197], v[116:119]
	v_mfma_f32_16x16x32_bf16 v[104:107], v[166:169], v[208:211], v[104:107]
	v_mfma_f32_16x16x32_bf16 v[100:103], v[174:177], v[208:211], v[100:103]
	v_mfma_f32_16x16x32_bf16 v[70:73], v[166:169], v[218:221], v[70:73]
	v_mfma_f32_16x16x32_bf16 v[66:69], v[174:177], v[218:221], v[66:69]
	s_setprio 0
	s_barrier
	s_add_i32 s46, s53, s9
	v_lshl_add_u64 v[198:199], v[198:199], 0, s[28:29]
	s_mov_b32 m0, s46
	ds_read_b128 v[178:181], v187 offset:49152
	ds_read_b128 v[182:185], v187 offset:50176
	ds_read_b128 v[190:193], v187 offset:51200
	ds_read_b128 v[194:197], v187 offset:52224
	ds_read_b128 v[204:207], v187 offset:53248
	ds_read_b128 v[208:211], v187 offset:54272
	ds_read_b128 v[214:217], v187 offset:55296
	ds_read_b128 v[218:221], v187 offset:56320
	global_load_lds_dwordx4 v[198:199], off
	s_add_i32 m0, s46, 0x2000
	s_add_u32 s44, s44, 0x40080
	v_lshl_add_u64 v[198:199], v[222:223], 0, s[28:29]
	s_addc_u32 s45, s45, 0
	s_add_i32 s46, s54, s9
	global_load_lds_dwordx4 v[198:199], off
	v_lshl_add_u64 v[198:199], s[44:45], 0, v[98:99]
	s_mov_b32 m0, s46
	s_nop 0
	global_load_lds_dwordx4 v[198:199], off
	v_lshl_add_u64 v[198:199], s[44:45], 0, v[152:153]
	s_add_i32 m0, s46, 0x2000
	s_nop 0
	global_load_lds_dwordx4 v[198:199], off
	s_setprio 1
	s_waitcnt vmcnt(6)
	s_waitcnt lgkmcnt(0)
	s_barrier
	v_mfma_f32_16x16x32_bf16 v[62:65], v[82:85], v[178:181], v[62:65]
	v_mfma_f32_16x16x32_bf16 v[58:61], v[90:93], v[178:181], v[58:61]
	v_mfma_f32_16x16x32_bf16 v[46:49], v[82:85], v[190:193], v[46:49]
	v_mfma_f32_16x16x32_bf16 v[42:45], v[90:93], v[190:193], v[42:45]
	v_mfma_f32_16x16x32_bf16 v[30:33], v[82:85], v[204:207], v[30:33]
	v_mfma_f32_16x16x32_bf16 v[26:29], v[90:93], v[204:207], v[26:29]
	v_mfma_f32_16x16x32_bf16 v[14:17], v[82:85], v[214:217], v[14:17]
	v_mfma_f32_16x16x32_bf16 v[10:13], v[90:93], v[214:217], v[10:13]
	v_mfma_f32_16x16x32_bf16 v[62:65], v[86:89], v[182:185], v[62:65]
	v_mfma_f32_16x16x32_bf16 v[58:61], v[94:97], v[182:185], v[58:61]
	v_mfma_f32_16x16x32_bf16 v[46:49], v[86:89], v[194:197], v[46:49]
	v_mfma_f32_16x16x32_bf16 v[42:45], v[94:97], v[194:197], v[42:45]
	v_mfma_f32_16x16x32_bf16 v[30:33], v[86:89], v[208:211], v[30:33]
	v_mfma_f32_16x16x32_bf16 v[26:29], v[94:97], v[208:211], v[26:29]
	v_mfma_f32_16x16x32_bf16 v[14:17], v[86:89], v[218:221], v[14:17]
	v_mfma_f32_16x16x32_bf16 v[10:13], v[94:97], v[218:221], v[10:13]
	s_setprio 0
	s_setprio 1
	v_mfma_f32_16x16x32_bf16 v[54:57], v[162:165], v[178:181], v[54:57]
	v_mfma_f32_16x16x32_bf16 v[50:53], v[170:173], v[178:181], v[50:53]
	v_mfma_f32_16x16x32_bf16 v[38:41], v[162:165], v[190:193], v[38:41]
	v_mfma_f32_16x16x32_bf16 v[34:37], v[170:173], v[190:193], v[34:37]
	v_mfma_f32_16x16x32_bf16 v[22:25], v[162:165], v[204:207], v[22:25]
	v_mfma_f32_16x16x32_bf16 v[18:21], v[170:173], v[204:207], v[18:21]
	v_mfma_f32_16x16x32_bf16 v[6:9], v[162:165], v[214:217], v[6:9]
	v_mfma_f32_16x16x32_bf16 v[2:5], v[170:173], v[214:217], v[2:5]
	v_mfma_f32_16x16x32_bf16 v[54:57], v[166:169], v[182:185], v[54:57]
	v_mfma_f32_16x16x32_bf16 v[50:53], v[174:177], v[182:185], v[50:53]
	v_mfma_f32_16x16x32_bf16 v[38:41], v[166:169], v[194:197], v[38:41]
	v_mfma_f32_16x16x32_bf16 v[34:37], v[174:177], v[194:197], v[34:37]
	v_mfma_f32_16x16x32_bf16 v[22:25], v[166:169], v[208:211], v[22:25]
	v_mfma_f32_16x16x32_bf16 v[18:21], v[174:177], v[208:211], v[18:21]
	v_mfma_f32_16x16x32_bf16 v[6:9], v[166:169], v[218:221], v[6:9]
	v_mfma_f32_16x16x32_bf16 v[2:5], v[174:177], v[218:221], v[2:5]
	s_setprio 0
	s_barrier
	s_add_i32 s52, s52, 2
	s_add_u32 s42, s42, 0x100
	s_addc_u32 s43, s43, 0
	s_add_u32 s50, s50, 0x100
	s_addc_u32 s51, s51, 0
	s_cmp_gt_u32 s52, 13
	s_cbranch_scc0 .LBB0_1328
	s_and_b64 vcc, exec, s[76:77]
	s_cbranch_vccz .LBB0_1331
	s_barrier

.LBB0_1529:
	s_add_u32 s50, s48, 0x100
	s_addc_u32 s51, s49, 0
	s_add_i32 s58, 0, 0x10000
	s_cmp_eq_u32 s57, 40
	s_cselect_b32 s55, s1, s51
	s_cselect_b32 s54, s0, s50
	s_cselect_b32 s53, s47, s56
	s_cselect_b32 s52, s46, s33
	s_add_i32 s59, 0, 0x14000
	v_add_u32_e32 v144, s58, v186
	v_add_u32_e32 v160, s59, v186
	ds_read_b128 v[132:135], v144
	ds_read_b128 v[136:139], v144 offset:1024
	ds_read_b128 v[140:143], v144 offset:2048
	ds_read_b128 v[144:147], v144 offset:3072
	ds_read_b128 v[148:151], v160
	ds_read_b128 v[152:155], v160 offset:1024
	ds_read_b128 v[156:159], v160 offset:2048
	ds_read_b128 v[160:163], v160 offset:3072
	v_lshl_add_u64 v[214:215], s[48:49], 0, v[174:175]
	s_add_i32 m0, s4, 0xc000
	ds_read_b128 v[164:167], v187
	ds_read_b128 v[178:181], v187 offset:1024
	ds_read_b128 v[182:185], v187 offset:2048
	ds_read_b128 v[188:191], v187 offset:3072
	ds_read_b128 v[192:195], v187 offset:4096
	ds_read_b128 v[196:199], v187 offset:5120
	ds_read_b128 v[204:207], v187 offset:6144
	ds_read_b128 v[208:211], v187 offset:7168
	global_load_lds_dwordx4 v[214:215], off
	v_lshl_add_u64 v[214:215], s[48:49], 0, v[176:177]
	s_add_i32 m0, s4, 0xe000
	s_nop 0
	global_load_lds_dwordx4 v[214:215], off
	s_setprio 1
	s_waitcnt vmcnt(8)
	s_waitcnt lgkmcnt(0)
	s_barrier
	v_mfma_f32_16x16x32_bf16 v[128:131], v[132:135], v[164:167], v[128:131]
	v_mfma_f32_16x16x32_bf16 v[124:127], v[140:143], v[164:167], v[124:127]
	v_mfma_f32_16x16x32_bf16 v[120:123], v[132:135], v[182:185], v[120:123]
	v_mfma_f32_16x16x32_bf16 v[116:119], v[140:143], v[182:185], v[116:119]
	v_mfma_f32_16x16x32_bf16 v[112:115], v[132:135], v[192:195], v[112:115]
	v_mfma_f32_16x16x32_bf16 v[108:111], v[140:143], v[192:195], v[108:111]
	v_mfma_f32_16x16x32_bf16 v[104:107], v[132:135], v[204:207], v[104:107]
	v_mfma_f32_16x16x32_bf16 v[100:103], v[140:143], v[204:207], v[100:103]
	v_mfma_f32_16x16x32_bf16 v[128:131], v[136:139], v[178:181], v[128:131]
	v_mfma_f32_16x16x32_bf16 v[124:127], v[144:147], v[178:181], v[124:127]
	v_mfma_f32_16x16x32_bf16 v[120:123], v[136:139], v[188:191], v[120:123]
	v_mfma_f32_16x16x32_bf16 v[116:119], v[144:147], v[188:191], v[116:119]
	v_mfma_f32_16x16x32_bf16 v[112:115], v[136:139], v[196:199], v[112:115]
	v_mfma_f32_16x16x32_bf16 v[108:111], v[144:147], v[196:199], v[108:111]
	v_mfma_f32_16x16x32_bf16 v[104:107], v[136:139], v[208:211], v[104:107]
	v_mfma_f32_16x16x32_bf16 v[100:103], v[144:147], v[208:211], v[100:103]
	s_setprio 0
	s_setprio 1
	v_mfma_f32_16x16x32_bf16 v[62:65], v[148:151], v[164:167], v[62:65]
	v_mfma_f32_16x16x32_bf16 v[58:61], v[156:159], v[164:167], v[58:61]
	v_mfma_f32_16x16x32_bf16 v[54:57], v[148:151], v[182:185], v[54:57]
	v_mfma_f32_16x16x32_bf16 v[50:53], v[156:159], v[182:185], v[50:53]
	v_mfma_f32_16x16x32_bf16 v[46:49], v[148:151], v[192:195], v[46:49]
	v_mfma_f32_16x16x32_bf16 v[42:45], v[156:159], v[192:195], v[42:45]
	v_mfma_f32_16x16x32_bf16 v[38:41], v[148:151], v[204:207], v[38:41]
	v_mfma_f32_16x16x32_bf16 v[34:37], v[156:159], v[204:207], v[34:37]
	v_mfma_f32_16x16x32_bf16 v[62:65], v[152:155], v[178:181], v[62:65]
	v_mfma_f32_16x16x32_bf16 v[58:61], v[160:163], v[178:181], v[58:61]
	v_mfma_f32_16x16x32_bf16 v[54:57], v[152:155], v[188:191], v[54:57]
	v_mfma_f32_16x16x32_bf16 v[50:53], v[160:163], v[188:191], v[50:53]
	v_mfma_f32_16x16x32_bf16 v[46:49], v[152:155], v[196:199], v[46:49]
	v_mfma_f32_16x16x32_bf16 v[42:45], v[160:163], v[196:199], v[42:45]
	v_mfma_f32_16x16x32_bf16 v[38:41], v[152:155], v[208:211], v[38:41]
	v_mfma_f32_16x16x32_bf16 v[34:37], v[160:163], v[208:211], v[34:37]
	s_setprio 0
	s_barrier
	s_add_i32 s48, s58, s2
	v_lshl_add_u64 v[214:215], s[52:53], 0, v[98:99]
	s_mov_b32 m0, s48
	ds_read_b128 v[164:167], v187 offset:16384
	ds_read_b128 v[178:181], v187 offset:17408
	ds_read_b128 v[182:185], v187 offset:18432
	ds_read_b128 v[188:191], v187 offset:19456
	ds_read_b128 v[192:195], v187 offset:20480
	ds_read_b128 v[196:199], v187 offset:21504
	ds_read_b128 v[204:207], v187 offset:22528
	ds_read_b128 v[208:211], v187 offset:23552
	global_load_lds_dwordx4 v[214:215], off
	s_add_i32 m0, s48, 0x2000
	s_add_u32 s48, s52, 0xb0000
	v_lshl_add_u64 v[216:217], s[52:53], 0, v[168:169]
	s_addc_u32 s49, s53, 0
	s_add_i32 s58, s59, s2
	global_load_lds_dwordx4 v[216:217], off
	v_lshl_add_u64 v[218:219], s[48:49], 0, v[98:99]
	s_mov_b32 m0, s58
	v_lshl_add_u64 v[220:221], s[54:55], 0, v[170:171]
	global_load_lds_dwordx4 v[218:219], off
	v_lshl_add_u64 v[218:219], s[48:49], 0, v[168:169]
	s_add_i32 m0, s58, 0x2000
	s_nop 0
	global_load_lds_dwordx4 v[218:219], off
	v_lshl_add_u64 v[218:219], s[54:55], 0, v[172:173]
	s_mov_b32 m0, s4
	s_nop 0
	global_load_lds_dwordx4 v[218:219], off
	s_mov_b32 m0, s7
	s_nop 0
	global_load_lds_dwordx4 v[220:221], off
	s_setprio 1
	s_waitcnt vmcnt(8)
	s_waitcnt lgkmcnt(0)
	s_barrier
	v_mfma_f32_16x16x32_bf16 v[94:97], v[132:135], v[164:167], v[94:97]
	v_mfma_f32_16x16x32_bf16 v[90:93], v[140:143], v[164:167], v[90:93]
	v_mfma_f32_16x16x32_bf16 v[86:89], v[132:135], v[182:185], v[86:89]
	v_mfma_f32_16x16x32_bf16 v[82:85], v[140:143], v[182:185], v[82:85]
	v_mfma_f32_16x16x32_bf16 v[78:81], v[132:135], v[192:195], v[78:81]
	v_mfma_f32_16x16x32_bf16 v[74:77], v[140:143], v[192:195], v[74:77]
	v_mfma_f32_16x16x32_bf16 v[70:73], v[132:135], v[204:207], v[70:73]
	v_mfma_f32_16x16x32_bf16 v[66:69], v[140:143], v[204:207], v[66:69]
	v_mfma_f32_16x16x32_bf16 v[94:97], v[136:139], v[178:181], v[94:97]
	v_mfma_f32_16x16x32_bf16 v[90:93], v[144:147], v[178:181], v[90:93]
	v_mfma_f32_16x16x32_bf16 v[86:89], v[136:139], v[188:191], v[86:89]
	v_mfma_f32_16x16x32_bf16 v[82:85], v[144:147], v[188:191], v[82:85]
	v_mfma_f32_16x16x32_bf16 v[78:81], v[136:139], v[196:199], v[78:81]
	v_mfma_f32_16x16x32_bf16 v[74:77], v[144:147], v[196:199], v[74:77]
	v_mfma_f32_16x16x32_bf16 v[70:73], v[136:139], v[208:211], v[70:73]
	v_mfma_f32_16x16x32_bf16 v[66:69], v[144:147], v[208:211], v[66:69]
	s_setprio 0
	s_setprio 1
	v_mfma_f32_16x16x32_bf16 v[30:33], v[148:151], v[164:167], v[30:33]
	v_mfma_f32_16x16x32_bf16 v[26:29], v[156:159], v[164:167], v[26:29]
	v_mfma_f32_16x16x32_bf16 v[22:25], v[148:151], v[182:185], v[22:25]
	v_mfma_f32_16x16x32_bf16 v[18:21], v[156:159], v[182:185], v[18:21]
	v_mfma_f32_16x16x32_bf16 v[14:17], v[148:151], v[192:195], v[14:17]
	v_mfma_f32_16x16x32_bf16 v[10:13], v[156:159], v[192:195], v[10:13]
	v_mfma_f32_16x16x32_bf16 v[6:9], v[148:151], v[204:207], v[6:9]
	v_mfma_f32_16x16x32_bf16 v[2:5], v[156:159], v[204:207], v[2:5]
	v_mfma_f32_16x16x32_bf16 v[30:33], v[152:155], v[178:181], v[30:33]
	v_mfma_f32_16x16x32_bf16 v[26:29], v[160:163], v[178:181], v[26:29]
	v_mfma_f32_16x16x32_bf16 v[22:25], v[152:155], v[188:191], v[22:25]
	v_mfma_f32_16x16x32_bf16 v[18:21], v[160:163], v[188:191], v[18:21]
	v_mfma_f32_16x16x32_bf16 v[14:17], v[152:155], v[196:199], v[14:17]
	v_mfma_f32_16x16x32_bf16 v[10:13], v[160:163], v[196:199], v[10:13]
	v_mfma_f32_16x16x32_bf16 v[6:9], v[152:155], v[208:211], v[6:9]
	v_mfma_f32_16x16x32_bf16 v[2:5], v[160:163], v[208:211], v[2:5]
	s_setprio 0
	s_barrier
	s_add_i32 s58, 0, 0x18000
	s_add_i32 s59, 0, 0x1c000
	v_add_u32_e32 v144, s58, v186
	v_add_u32_e32 v160, s59, v186
	ds_read_b128 v[132:135], v144
	ds_read_b128 v[136:139], v144 offset:1024
	ds_read_b128 v[140:143], v144 offset:2048
	ds_read_b128 v[144:147], v144 offset:3072
	ds_read_b128 v[148:151], v160
	ds_read_b128 v[152:155], v160 offset:1024
	ds_read_b128 v[156:159], v160 offset:2048
	ds_read_b128 v[160:163], v160 offset:3072
	s_add_u32 s48, s54, 0xb0000
	s_addc_u32 s49, s55, 0
	s_mov_b32 m0, s8
	v_lshl_add_u64 v[222:223], s[48:49], 0, v[172:173]
	ds_read_b128 v[164:167], v187 offset:32768
	ds_read_b128 v[178:181], v187 offset:33792
	ds_read_b128 v[182:185], v187 offset:34816
	ds_read_b128 v[188:191], v187 offset:35840
	ds_read_b128 v[192:195], v187 offset:36864
	ds_read_b128 v[196:199], v187 offset:37888
	ds_read_b128 v[204:207], v187 offset:38912
	ds_read_b128 v[208:211], v187 offset:39936
	global_load_lds_dwordx4 v[222:223], off
	v_lshl_add_u64 v[222:223], s[48:49], 0, v[170:171]
	s_mov_b32 m0, s9
	s_nop 0
	global_load_lds_dwordx4 v[222:223], off
	s_setprio 1
	s_waitcnt vmcnt(8)
	s_waitcnt lgkmcnt(0)
	s_barrier
	v_mfma_f32_16x16x32_bf16 v[128:131], v[132:135], v[164:167], v[128:131]
	v_mfma_f32_16x16x32_bf16 v[124:127], v[140:143], v[164:167], v[124:127]
	v_mfma_f32_16x16x32_bf16 v[120:123], v[132:135], v[182:185], v[120:123]
	v_mfma_f32_16x16x32_bf16 v[116:119], v[140:143], v[182:185], v[116:119]
	v_mfma_f32_16x16x32_bf16 v[112:115], v[132:135], v[192:195], v[112:115]
	v_mfma_f32_16x16x32_bf16 v[108:111], v[140:143], v[192:195], v[108:111]
	v_mfma_f32_16x16x32_bf16 v[104:107], v[132:135], v[204:207], v[104:107]
	v_mfma_f32_16x16x32_bf16 v[100:103], v[140:143], v[204:207], v[100:103]
	v_mfma_f32_16x16x32_bf16 v[128:131], v[136:139], v[178:181], v[128:131]
	v_mfma_f32_16x16x32_bf16 v[124:127], v[144:147], v[178:181], v[124:127]
	v_mfma_f32_16x16x32_bf16 v[120:123], v[136:139], v[188:191], v[120:123]
	v_mfma_f32_16x16x32_bf16 v[116:119], v[144:147], v[188:191], v[116:119]
	v_mfma_f32_16x16x32_bf16 v[112:115], v[136:139], v[196:199], v[112:115]
	v_mfma_f32_16x16x32_bf16 v[108:111], v[144:147], v[196:199], v[108:111]
	v_mfma_f32_16x16x32_bf16 v[104:107], v[136:139], v[208:211], v[104:107]
	v_mfma_f32_16x16x32_bf16 v[100:103], v[144:147], v[208:211], v[100:103]
	s_setprio 0
	s_setprio 1
	v_mfma_f32_16x16x32_bf16 v[62:65], v[148:151], v[164:167], v[62:65]
	v_mfma_f32_16x16x32_bf16 v[58:61], v[156:159], v[164:167], v[58:61]
	v_mfma_f32_16x16x32_bf16 v[54:57], v[148:151], v[182:185], v[54:57]
	v_mfma_f32_16x16x32_bf16 v[50:53], v[156:159], v[182:185], v[50:53]
	v_mfma_f32_16x16x32_bf16 v[46:49], v[148:151], v[192:195], v[46:49]
	v_mfma_f32_16x16x32_bf16 v[42:45], v[156:159], v[192:195], v[42:45]
	v_mfma_f32_16x16x32_bf16 v[38:41], v[148:151], v[204:207], v[38:41]
	v_mfma_f32_16x16x32_bf16 v[34:37], v[156:159], v[204:207], v[34:37]
	v_mfma_f32_16x16x32_bf16 v[62:65], v[152:155], v[178:181], v[62:65]
	v_mfma_f32_16x16x32_bf16 v[58:61], v[160:163], v[178:181], v[58:61]
	v_mfma_f32_16x16x32_bf16 v[54:57], v[152:155], v[188:191], v[54:57]
	v_mfma_f32_16x16x32_bf16 v[50:53], v[160:163], v[188:191], v[50:53]
	v_mfma_f32_16x16x32_bf16 v[46:49], v[152:155], v[196:199], v[46:49]
	v_mfma_f32_16x16x32_bf16 v[42:45], v[160:163], v[196:199], v[42:45]
	v_mfma_f32_16x16x32_bf16 v[38:41], v[152:155], v[208:211], v[38:41]
	v_mfma_f32_16x16x32_bf16 v[34:37], v[160:163], v[208:211], v[34:37]
	s_setprio 0
	s_barrier
	s_add_i32 s48, s58, s2
	v_lshl_add_u64 v[214:215], v[214:215], 0, s[28:29]
	s_mov_b32 m0, s48
	ds_read_b128 v[164:167], v187 offset:49152
	ds_read_b128 v[178:181], v187 offset:50176
	ds_read_b128 v[182:185], v187 offset:51200
	ds_read_b128 v[188:191], v187 offset:52224
	ds_read_b128 v[192:195], v187 offset:53248
	ds_read_b128 v[196:199], v187 offset:54272
	ds_read_b128 v[204:207], v187 offset:55296
	ds_read_b128 v[208:211], v187 offset:56320
	global_load_lds_dwordx4 v[214:215], off
	s_add_i32 m0, s48, 0x2000
	s_add_u32 s48, s52, 0xb0080
	v_lshl_add_u64 v[214:215], v[216:217], 0, s[28:29]
	s_addc_u32 s49, s53, 0
	s_add_i32 s52, s59, s2
	global_load_lds_dwordx4 v[214:215], off
	v_lshl_add_u64 v[214:215], s[48:49], 0, v[98:99]
	s_mov_b32 m0, s52
	s_nop 0
	global_load_lds_dwordx4 v[214:215], off
	v_lshl_add_u64 v[214:215], s[48:49], 0, v[168:169]
	s_add_i32 m0, s52, 0x2000
	s_nop 0
	global_load_lds_dwordx4 v[214:215], off
	v_lshl_add_u64 v[214:215], v[218:219], 0, s[28:29]
	s_mov_b32 m0, s12
	s_nop 0
	global_load_lds_dwordx4 v[214:215], off
	v_lshl_add_u64 v[214:215], v[220:221], 0, s[28:29]
	s_mov_b32 m0, s13
	s_nop 0
	global_load_lds_dwordx4 v[214:215], off
	s_setprio 1
	s_waitcnt vmcnt(8)
	s_waitcnt lgkmcnt(0)
	s_barrier
	v_mfma_f32_16x16x32_bf16 v[94:97], v[132:135], v[164:167], v[94:97]
	v_mfma_f32_16x16x32_bf16 v[90:93], v[140:143], v[164:167], v[90:93]
	v_mfma_f32_16x16x32_bf16 v[86:89], v[132:135], v[182:185], v[86:89]
	v_mfma_f32_16x16x32_bf16 v[82:85], v[140:143], v[182:185], v[82:85]
	v_mfma_f32_16x16x32_bf16 v[78:81], v[132:135], v[192:195], v[78:81]
	v_mfma_f32_16x16x32_bf16 v[74:77], v[140:143], v[192:195], v[74:77]
	v_mfma_f32_16x16x32_bf16 v[70:73], v[132:135], v[204:207], v[70:73]
	v_mfma_f32_16x16x32_bf16 v[66:69], v[140:143], v[204:207], v[66:69]
	v_mfma_f32_16x16x32_bf16 v[94:97], v[136:139], v[178:181], v[94:97]
	v_mfma_f32_16x16x32_bf16 v[90:93], v[144:147], v[178:181], v[90:93]
	v_mfma_f32_16x16x32_bf16 v[86:89], v[136:139], v[188:191], v[86:89]
	v_mfma_f32_16x16x32_bf16 v[82:85], v[144:147], v[188:191], v[82:85]
	v_mfma_f32_16x16x32_bf16 v[78:81], v[136:139], v[196:199], v[78:81]
	v_mfma_f32_16x16x32_bf16 v[74:77], v[144:147], v[196:199], v[74:77]
	v_mfma_f32_16x16x32_bf16 v[70:73], v[136:139], v[208:211], v[70:73]
	v_mfma_f32_16x16x32_bf16 v[66:69], v[144:147], v[208:211], v[66:69]
	s_setprio 0
	s_setprio 1
	v_mfma_f32_16x16x32_bf16 v[30:33], v[148:151], v[164:167], v[30:33]
	v_mfma_f32_16x16x32_bf16 v[26:29], v[156:159], v[164:167], v[26:29]
	v_mfma_f32_16x16x32_bf16 v[22:25], v[148:151], v[182:185], v[22:25]
	v_mfma_f32_16x16x32_bf16 v[18:21], v[156:159], v[182:185], v[18:21]
	v_mfma_f32_16x16x32_bf16 v[14:17], v[148:151], v[192:195], v[14:17]
	v_mfma_f32_16x16x32_bf16 v[10:13], v[156:159], v[192:195], v[10:13]
	v_mfma_f32_16x16x32_bf16 v[6:9], v[148:151], v[204:207], v[6:9]
	v_mfma_f32_16x16x32_bf16 v[2:5], v[156:159], v[204:207], v[2:5]
	v_mfma_f32_16x16x32_bf16 v[30:33], v[152:155], v[178:181], v[30:33]
	v_mfma_f32_16x16x32_bf16 v[26:29], v[160:163], v[178:181], v[26:29]
	v_mfma_f32_16x16x32_bf16 v[22:25], v[152:155], v[188:191], v[22:25]
	v_mfma_f32_16x16x32_bf16 v[18:21], v[160:163], v[188:191], v[18:21]
	v_mfma_f32_16x16x32_bf16 v[14:17], v[152:155], v[196:199], v[14:17]
	v_mfma_f32_16x16x32_bf16 v[10:13], v[160:163], v[196:199], v[10:13]
	v_mfma_f32_16x16x32_bf16 v[6:9], v[152:155], v[208:211], v[6:9]
	v_mfma_f32_16x16x32_bf16 v[2:5], v[160:163], v[208:211], v[2:5]
	s_setprio 0
	s_barrier
	s_add_i32 s57, s57, 2
	s_add_u32 s33, s33, 0x100
	s_addc_u32 s56, s56, 0
	s_cmp_gt_u32 s57, 41
	s_mov_b64 s[48:49], s[50:51]
	s_cbranch_scc0 .LBB0_1529
	s_and_b64 vcc, exec, s[44:45]
	s_cbranch_vccz .LBB0_1532
	s_barrier

.LBB0_1553:
	s_add_i32 s63, s54, 2
	s_add_u32 s52, s50, 0x100
	s_addc_u32 s53, s51, 0
	s_add_i32 s64, 0, 0x10000
	s_cmp_eq_u32 s60, s54
	s_cselect_b32 s57, s45, s53
	s_cselect_b32 s56, s44, s52
	s_cselect_b32 s55, s47, s62
	s_cselect_b32 s54, s46, s61
	s_add_i32 s65, 0, 0x14000
	v_add_u32_e32 v144, s64, v198
	v_add_u32_e32 v160, s65, v198
	s_waitcnt lgkmcnt(0)
	ds_read_b128 v[132:135], v144
	ds_read_b128 v[136:139], v144 offset:1024
	ds_read_b128 v[140:143], v144 offset:2048
	ds_read_b128 v[144:147], v144 offset:3072
	ds_read_b128 v[148:151], v160
	ds_read_b128 v[152:155], v160 offset:1024
	ds_read_b128 v[156:159], v160 offset:2048
	ds_read_b128 v[160:163], v160 offset:3072
	v_lshl_add_u64 v[214:215], s[50:51], 0, v[178:179]
	s_add_i32 m0, s4, 0xc000
	ds_read_b128 v[164:167], v199
	ds_read_b128 v[168:171], v199 offset:1024
	ds_read_b128 v[182:185], v199 offset:2048
	ds_read_b128 v[186:189], v199 offset:3072
	ds_read_b128 v[190:193], v199 offset:4096
	ds_read_b128 v[194:197], v199 offset:5120
	ds_read_b128 v[204:207], v199 offset:6144
	ds_read_b128 v[208:211], v199 offset:7168
	global_load_lds_dwordx4 v[214:215], off
	v_lshl_add_u64 v[214:215], s[50:51], 0, v[180:181]
	s_add_i32 m0, s4, 0xe000
	s_nop 0
	global_load_lds_dwordx4 v[214:215], off
	s_setprio 1
	s_waitcnt vmcnt(8)
	s_waitcnt lgkmcnt(0)
	s_barrier
	v_mfma_f32_16x16x32_bf16 v[128:131], v[132:135], v[164:167], v[128:131]
	v_mfma_f32_16x16x32_bf16 v[124:127], v[140:143], v[164:167], v[124:127]
	v_mfma_f32_16x16x32_bf16 v[120:123], v[132:135], v[182:185], v[120:123]
	v_mfma_f32_16x16x32_bf16 v[116:119], v[140:143], v[182:185], v[116:119]
	v_mfma_f32_16x16x32_bf16 v[104:107], v[132:135], v[190:193], v[104:107]
	v_mfma_f32_16x16x32_bf16 v[100:103], v[140:143], v[190:193], v[100:103]
	v_mfma_f32_16x16x32_bf16 v[86:89], v[132:135], v[204:207], v[86:89]
	v_mfma_f32_16x16x32_bf16 v[82:85], v[140:143], v[204:207], v[82:85]
	v_mfma_f32_16x16x32_bf16 v[128:131], v[136:139], v[168:171], v[128:131]
	v_mfma_f32_16x16x32_bf16 v[124:127], v[144:147], v[168:171], v[124:127]
	v_mfma_f32_16x16x32_bf16 v[120:123], v[136:139], v[186:189], v[120:123]
	v_mfma_f32_16x16x32_bf16 v[116:119], v[144:147], v[186:189], v[116:119]
	v_mfma_f32_16x16x32_bf16 v[104:107], v[136:139], v[194:197], v[104:107]
	v_mfma_f32_16x16x32_bf16 v[100:103], v[144:147], v[194:197], v[100:103]
	v_mfma_f32_16x16x32_bf16 v[86:89], v[136:139], v[208:211], v[86:89]
	v_mfma_f32_16x16x32_bf16 v[82:85], v[144:147], v[208:211], v[82:85]
	s_setprio 0
	s_setprio 1
	v_mfma_f32_16x16x32_bf16 v[112:115], v[148:151], v[164:167], v[112:115]
	v_mfma_f32_16x16x32_bf16 v[108:111], v[156:159], v[164:167], v[108:111]
	v_mfma_f32_16x16x32_bf16 v[94:97], v[148:151], v[182:185], v[94:97]
	v_mfma_f32_16x16x32_bf16 v[90:93], v[156:159], v[182:185], v[90:93]
	v_mfma_f32_16x16x32_bf16 v[78:81], v[148:151], v[190:193], v[78:81]
	v_mfma_f32_16x16x32_bf16 v[74:77], v[156:159], v[190:193], v[74:77]
	v_mfma_f32_16x16x32_bf16 v[70:73], v[148:151], v[204:207], v[70:73]
	v_mfma_f32_16x16x32_bf16 v[66:69], v[156:159], v[204:207], v[66:69]
	v_mfma_f32_16x16x32_bf16 v[112:115], v[152:155], v[168:171], v[112:115]
	v_mfma_f32_16x16x32_bf16 v[108:111], v[160:163], v[168:171], v[108:111]
	v_mfma_f32_16x16x32_bf16 v[94:97], v[152:155], v[186:189], v[94:97]
	v_mfma_f32_16x16x32_bf16 v[90:93], v[160:163], v[186:189], v[90:93]
	v_mfma_f32_16x16x32_bf16 v[78:81], v[152:155], v[194:197], v[78:81]
	v_mfma_f32_16x16x32_bf16 v[74:77], v[160:163], v[194:197], v[74:77]
	v_mfma_f32_16x16x32_bf16 v[70:73], v[152:155], v[208:211], v[70:73]
	v_mfma_f32_16x16x32_bf16 v[66:69], v[160:163], v[208:211], v[66:69]
	s_setprio 0
	s_barrier
	s_add_i32 s50, s64, s2
	v_lshl_add_u64 v[214:215], s[54:55], 0, v[98:99]
	s_mov_b32 m0, s50
	ds_read_b128 v[164:167], v199 offset:16384
	ds_read_b128 v[168:171], v199 offset:17408
	ds_read_b128 v[182:185], v199 offset:18432
	ds_read_b128 v[186:189], v199 offset:19456
	ds_read_b128 v[190:193], v199 offset:20480
	ds_read_b128 v[194:197], v199 offset:21504
	ds_read_b128 v[204:207], v199 offset:22528
	ds_read_b128 v[208:211], v199 offset:23552
	global_load_lds_dwordx4 v[214:215], off
	s_add_i32 m0, s50, 0x2000
	s_add_u32 s50, s54, 0xb0000
	v_lshl_add_u64 v[216:217], s[54:55], 0, v[172:173]
	s_addc_u32 s51, s55, 0
	s_add_i32 s64, s65, s2
	global_load_lds_dwordx4 v[216:217], off
	v_lshl_add_u64 v[218:219], s[50:51], 0, v[98:99]
	s_mov_b32 m0, s64
	v_lshl_add_u64 v[220:221], s[56:57], 0, v[174:175]
	global_load_lds_dwordx4 v[218:219], off
	v_lshl_add_u64 v[218:219], s[50:51], 0, v[172:173]
	s_add_i32 m0, s64, 0x2000
	s_nop 0
	global_load_lds_dwordx4 v[218:219], off
	v_lshl_add_u64 v[218:219], s[56:57], 0, v[176:177]
	s_mov_b32 m0, s4
	s_nop 0
	global_load_lds_dwordx4 v[218:219], off
	s_mov_b32 m0, s7
	s_nop 0
	global_load_lds_dwordx4 v[220:221], off
	s_setprio 1
	s_waitcnt vmcnt(8)
	s_waitcnt lgkmcnt(0)
	s_barrier
	v_mfma_f32_16x16x32_bf16 v[62:65], v[132:135], v[164:167], v[62:65]
	v_mfma_f32_16x16x32_bf16 v[58:61], v[140:143], v[164:167], v[58:61]
	v_mfma_f32_16x16x32_bf16 v[54:57], v[132:135], v[182:185], v[54:57]
	v_mfma_f32_16x16x32_bf16 v[50:53], v[140:143], v[182:185], v[50:53]
	v_mfma_f32_16x16x32_bf16 v[38:41], v[132:135], v[190:193], v[38:41]
	v_mfma_f32_16x16x32_bf16 v[34:37], v[140:143], v[190:193], v[34:37]
	v_mfma_f32_16x16x32_bf16 v[22:25], v[132:135], v[204:207], v[22:25]
	v_mfma_f32_16x16x32_bf16 v[18:21], v[140:143], v[204:207], v[18:21]
	v_mfma_f32_16x16x32_bf16 v[62:65], v[136:139], v[168:171], v[62:65]
	v_mfma_f32_16x16x32_bf16 v[58:61], v[144:147], v[168:171], v[58:61]
	v_mfma_f32_16x16x32_bf16 v[54:57], v[136:139], v[186:189], v[54:57]
	v_mfma_f32_16x16x32_bf16 v[50:53], v[144:147], v[186:189], v[50:53]
	v_mfma_f32_16x16x32_bf16 v[38:41], v[136:139], v[194:197], v[38:41]
	v_mfma_f32_16x16x32_bf16 v[34:37], v[144:147], v[194:197], v[34:37]
	v_mfma_f32_16x16x32_bf16 v[22:25], v[136:139], v[208:211], v[22:25]
	v_mfma_f32_16x16x32_bf16 v[18:21], v[144:147], v[208:211], v[18:21]
	s_setprio 0
	s_setprio 1
	v_mfma_f32_16x16x32_bf16 v[46:49], v[148:151], v[164:167], v[46:49]
	v_mfma_f32_16x16x32_bf16 v[42:45], v[156:159], v[164:167], v[42:45]
	v_mfma_f32_16x16x32_bf16 v[30:33], v[148:151], v[182:185], v[30:33]
	v_mfma_f32_16x16x32_bf16 v[26:29], v[156:159], v[182:185], v[26:29]
	v_mfma_f32_16x16x32_bf16 v[14:17], v[148:151], v[190:193], v[14:17]
	v_mfma_f32_16x16x32_bf16 v[10:13], v[156:159], v[190:193], v[10:13]
	v_mfma_f32_16x16x32_bf16 v[6:9], v[148:151], v[204:207], v[6:9]
	v_mfma_f32_16x16x32_bf16 v[2:5], v[156:159], v[204:207], v[2:5]
	v_mfma_f32_16x16x32_bf16 v[46:49], v[152:155], v[168:171], v[46:49]
	v_mfma_f32_16x16x32_bf16 v[42:45], v[160:163], v[168:171], v[42:45]
	v_mfma_f32_16x16x32_bf16 v[30:33], v[152:155], v[186:189], v[30:33]
	v_mfma_f32_16x16x32_bf16 v[26:29], v[160:163], v[186:189], v[26:29]
	v_mfma_f32_16x16x32_bf16 v[14:17], v[152:155], v[194:197], v[14:17]
	v_mfma_f32_16x16x32_bf16 v[10:13], v[160:163], v[194:197], v[10:13]
	v_mfma_f32_16x16x32_bf16 v[6:9], v[152:155], v[208:211], v[6:9]
	v_mfma_f32_16x16x32_bf16 v[2:5], v[160:163], v[208:211], v[2:5]
	s_setprio 0
	s_barrier
	s_add_i32 s64, 0, 0x18000
	s_add_i32 s65, 0, 0x1c000
	v_add_u32_e32 v144, s64, v198
	v_add_u32_e32 v160, s65, v198
	ds_read_b128 v[132:135], v144
	ds_read_b128 v[136:139], v144 offset:1024
	ds_read_b128 v[140:143], v144 offset:2048
	ds_read_b128 v[144:147], v144 offset:3072
	ds_read_b128 v[148:151], v160
	ds_read_b128 v[152:155], v160 offset:1024
	ds_read_b128 v[156:159], v160 offset:2048
	ds_read_b128 v[160:163], v160 offset:3072
	s_add_u32 s50, s56, 0xb0000
	s_addc_u32 s51, s57, 0
	s_mov_b32 m0, s8
	v_lshl_add_u64 v[222:223], s[50:51], 0, v[176:177]
	ds_read_b128 v[164:167], v199 offset:32768
	ds_read_b128 v[168:171], v199 offset:33792
	ds_read_b128 v[182:185], v199 offset:34816
	ds_read_b128 v[186:189], v199 offset:35840
	ds_read_b128 v[190:193], v199 offset:36864
	ds_read_b128 v[194:197], v199 offset:37888
	ds_read_b128 v[204:207], v199 offset:38912
	ds_read_b128 v[208:211], v199 offset:39936
	global_load_lds_dwordx4 v[222:223], off
	v_lshl_add_u64 v[222:223], s[50:51], 0, v[174:175]
	s_mov_b32 m0, s9
	s_nop 0
	global_load_lds_dwordx4 v[222:223], off
	s_setprio 1
	s_waitcnt vmcnt(8)
	s_waitcnt lgkmcnt(0)
	s_barrier
	v_mfma_f32_16x16x32_bf16 v[128:131], v[132:135], v[164:167], v[128:131]
	v_mfma_f32_16x16x32_bf16 v[124:127], v[140:143], v[164:167], v[124:127]
	v_mfma_f32_16x16x32_bf16 v[120:123], v[132:135], v[182:185], v[120:123]
	v_mfma_f32_16x16x32_bf16 v[116:119], v[140:143], v[182:185], v[116:119]
	v_mfma_f32_16x16x32_bf16 v[104:107], v[132:135], v[190:193], v[104:107]
	v_mfma_f32_16x16x32_bf16 v[100:103], v[140:143], v[190:193], v[100:103]
	v_mfma_f32_16x16x32_bf16 v[86:89], v[132:135], v[204:207], v[86:89]
	v_mfma_f32_16x16x32_bf16 v[82:85], v[140:143], v[204:207], v[82:85]
	v_mfma_f32_16x16x32_bf16 v[128:131], v[136:139], v[168:171], v[128:131]
	v_mfma_f32_16x16x32_bf16 v[124:127], v[144:147], v[168:171], v[124:127]
	v_mfma_f32_16x16x32_bf16 v[120:123], v[136:139], v[186:189], v[120:123]
	v_mfma_f32_16x16x32_bf16 v[116:119], v[144:147], v[186:189], v[116:119]
	v_mfma_f32_16x16x32_bf16 v[104:107], v[136:139], v[194:197], v[104:107]
	v_mfma_f32_16x16x32_bf16 v[100:103], v[144:147], v[194:197], v[100:103]
	v_mfma_f32_16x16x32_bf16 v[86:89], v[136:139], v[208:211], v[86:89]
	v_mfma_f32_16x16x32_bf16 v[82:85], v[144:147], v[208:211], v[82:85]
	s_setprio 0
	s_setprio 1
	v_mfma_f32_16x16x32_bf16 v[112:115], v[148:151], v[164:167], v[112:115]
	v_mfma_f32_16x16x32_bf16 v[108:111], v[156:159], v[164:167], v[108:111]
	v_mfma_f32_16x16x32_bf16 v[94:97], v[148:151], v[182:185], v[94:97]
	v_mfma_f32_16x16x32_bf16 v[90:93], v[156:159], v[182:185], v[90:93]
	v_mfma_f32_16x16x32_bf16 v[78:81], v[148:151], v[190:193], v[78:81]
	v_mfma_f32_16x16x32_bf16 v[74:77], v[156:159], v[190:193], v[74:77]
	v_mfma_f32_16x16x32_bf16 v[70:73], v[148:151], v[204:207], v[70:73]
	v_mfma_f32_16x16x32_bf16 v[66:69], v[156:159], v[204:207], v[66:69]
	v_mfma_f32_16x16x32_bf16 v[112:115], v[152:155], v[168:171], v[112:115]
	v_mfma_f32_16x16x32_bf16 v[108:111], v[160:163], v[168:171], v[108:111]
	v_mfma_f32_16x16x32_bf16 v[94:97], v[152:155], v[186:189], v[94:97]
	v_mfma_f32_16x16x32_bf16 v[90:93], v[160:163], v[186:189], v[90:93]
	v_mfma_f32_16x16x32_bf16 v[78:81], v[152:155], v[194:197], v[78:81]
	v_mfma_f32_16x16x32_bf16 v[74:77], v[160:163], v[194:197], v[74:77]
	v_mfma_f32_16x16x32_bf16 v[70:73], v[152:155], v[208:211], v[70:73]
	v_mfma_f32_16x16x32_bf16 v[66:69], v[160:163], v[208:211], v[66:69]
	s_setprio 0
	s_barrier
	s_add_i32 s50, s64, s2
	v_lshl_add_u64 v[214:215], v[214:215], 0, s[28:29]
	s_mov_b32 m0, s50
	ds_read_b128 v[164:167], v199 offset:49152
	ds_read_b128 v[168:171], v199 offset:50176
	ds_read_b128 v[182:185], v199 offset:51200
	ds_read_b128 v[186:189], v199 offset:52224
	ds_read_b128 v[190:193], v199 offset:53248
	ds_read_b128 v[194:197], v199 offset:54272
	ds_read_b128 v[204:207], v199 offset:55296
	ds_read_b128 v[208:211], v199 offset:56320
	global_load_lds_dwordx4 v[214:215], off
	s_add_i32 m0, s50, 0x2000
	s_add_u32 s50, s54, 0xb0080
	v_lshl_add_u64 v[214:215], v[216:217], 0, s[28:29]
	s_addc_u32 s51, s55, 0
	s_add_i32 s54, s65, s2
	global_load_lds_dwordx4 v[214:215], off
	v_lshl_add_u64 v[214:215], s[50:51], 0, v[98:99]
	s_mov_b32 m0, s54
	s_nop 0
	global_load_lds_dwordx4 v[214:215], off
	v_lshl_add_u64 v[214:215], s[50:51], 0, v[172:173]
	s_add_i32 m0, s54, 0x2000
	s_nop 0
	global_load_lds_dwordx4 v[214:215], off
	v_lshl_add_u64 v[214:215], v[218:219], 0, s[28:29]
	s_mov_b32 m0, s12
	s_nop 0
	global_load_lds_dwordx4 v[214:215], off
	v_lshl_add_u64 v[214:215], v[220:221], 0, s[28:29]
	s_mov_b32 m0, s13
	s_nop 0
	global_load_lds_dwordx4 v[214:215], off
	s_setprio 1
	s_waitcnt vmcnt(8)
	s_waitcnt lgkmcnt(0)
	s_barrier
	v_mfma_f32_16x16x32_bf16 v[62:65], v[132:135], v[164:167], v[62:65]
	v_mfma_f32_16x16x32_bf16 v[58:61], v[140:143], v[164:167], v[58:61]
	v_mfma_f32_16x16x32_bf16 v[54:57], v[132:135], v[182:185], v[54:57]
	v_mfma_f32_16x16x32_bf16 v[50:53], v[140:143], v[182:185], v[50:53]
	v_mfma_f32_16x16x32_bf16 v[38:41], v[132:135], v[190:193], v[38:41]
	v_mfma_f32_16x16x32_bf16 v[34:37], v[140:143], v[190:193], v[34:37]
	v_mfma_f32_16x16x32_bf16 v[22:25], v[132:135], v[204:207], v[22:25]
	v_mfma_f32_16x16x32_bf16 v[18:21], v[140:143], v[204:207], v[18:21]
	v_mfma_f32_16x16x32_bf16 v[62:65], v[136:139], v[168:171], v[62:65]
	v_mfma_f32_16x16x32_bf16 v[58:61], v[144:147], v[168:171], v[58:61]
	v_mfma_f32_16x16x32_bf16 v[54:57], v[136:139], v[186:189], v[54:57]
	v_mfma_f32_16x16x32_bf16 v[50:53], v[144:147], v[186:189], v[50:53]
	v_mfma_f32_16x16x32_bf16 v[38:41], v[136:139], v[194:197], v[38:41]
	v_mfma_f32_16x16x32_bf16 v[34:37], v[144:147], v[194:197], v[34:37]
	v_mfma_f32_16x16x32_bf16 v[22:25], v[136:139], v[208:211], v[22:25]
	v_mfma_f32_16x16x32_bf16 v[18:21], v[144:147], v[208:211], v[18:21]
	s_setprio 0
	s_setprio 1
	v_mfma_f32_16x16x32_bf16 v[46:49], v[148:151], v[164:167], v[46:49]
	v_mfma_f32_16x16x32_bf16 v[42:45], v[156:159], v[164:167], v[42:45]
	v_mfma_f32_16x16x32_bf16 v[30:33], v[148:151], v[182:185], v[30:33]
	v_mfma_f32_16x16x32_bf16 v[26:29], v[156:159], v[182:185], v[26:29]
	v_mfma_f32_16x16x32_bf16 v[14:17], v[148:151], v[190:193], v[14:17]
	v_mfma_f32_16x16x32_bf16 v[10:13], v[156:159], v[190:193], v[10:13]
	v_mfma_f32_16x16x32_bf16 v[6:9], v[148:151], v[204:207], v[6:9]
	v_mfma_f32_16x16x32_bf16 v[2:5], v[156:159], v[204:207], v[2:5]
	v_mfma_f32_16x16x32_bf16 v[46:49], v[152:155], v[168:171], v[46:49]
	v_mfma_f32_16x16x32_bf16 v[42:45], v[160:163], v[168:171], v[42:45]
	v_mfma_f32_16x16x32_bf16 v[30:33], v[152:155], v[186:189], v[30:33]
	v_mfma_f32_16x16x32_bf16 v[26:29], v[160:163], v[186:189], v[26:29]
	v_mfma_f32_16x16x32_bf16 v[14:17], v[152:155], v[194:197], v[14:17]
	v_mfma_f32_16x16x32_bf16 v[10:13], v[160:163], v[194:197], v[10:13]
	v_mfma_f32_16x16x32_bf16 v[6:9], v[152:155], v[208:211], v[6:9]
	v_mfma_f32_16x16x32_bf16 v[2:5], v[160:163], v[208:211], v[2:5]
	s_setprio 0
	s_barrier
	s_add_u32 s61, s61, 0x100
	s_addc_u32 s62, s62, 0
	s_cmp_ge_i32 s63, s59
	s_mov_b64 s[50:51], s[52:53]
	s_mov_b32 s54, s63
	s_cbranch_scc0 .LBB0_1553
	s_and_b64 vcc, exec, s[42:43]
	s_cbranch_vccz .LBB0_1556
	s_barrier
